# chunk-record stores marked nt (streamed once, read much later by the scan DMA)
# speedup vs baseline: 1.1729x; 1.0074x over previous
.LBB0_1003:
	s_or_b64 exec, exec, s[72:73]
	v_add_u32_e32 v46, 0x4800, v120
	s_waitcnt lgkmcnt(0)
	ds_read_b64 v[44:45], v130 offset:18432
	ds_read2_b64 v[46:49], v46 offset0:4 offset1:8
	v_add_u32_e32 v56, 0x7000, v120
	ds_read2_b64 v[50:53], v56 offset0:160 offset1:164
	v_lshl_add_u64 v[54:55], v[88:89], 0, v[142:143]
	s_waitcnt lgkmcnt(1)
	global_store_dwordx4 v[54:55], v[44:47], off nt
	s_waitcnt lgkmcnt(0)
	global_store_dwordx4 v[54:55], v[50:53], off offset:2048 nt
	ds_read_b64 v[46:47], v120 offset:18528
	ds_read2_b64 v[50:53], v56 offset0:168 offset1:172
	v_mov_b32_e32 v44, v48
	v_mov_b32_e32 v45, v49
	s_waitcnt lgkmcnt(1)
	global_store_dwordx4 v[54:55], v[44:47], off offset:1024 nt
	s_waitcnt lgkmcnt(0)
	global_store_dwordx4 v[54:55], v[50:53], off offset:3072 nt
	ds_read_b128 v[44:47], v106 offset:21760
	v_add_co_u32_e32 v48, vcc, 0x2000, v54
	s_add_i32 s26, s26, 8
	s_nop 0
	v_addc_co_u32_e32 v49, vcc, 0, v55, vcc
	s_waitcnt lgkmcnt(0)
	global_store_dwordx4 v[48:49], v[44:47], off nt
	ds_read_b128 v[44:47], v106 offset:20736
	s_cmp_lg_u32 s26, 64
	v_mov_b32_e32 v50, v155
	s_waitcnt lgkmcnt(0)
	global_store_dwordx4 v[48:49], v[44:47], off offset:1024 nt
	s_waitcnt lgkmcnt(0)
	s_cbranch_scc0 .LBB0_998

.LBB0_1026:
	s_or_b64 exec, exec, s[58:59]
	s_waitcnt lgkmcnt(0)
	ds_read_u16 v0, v107 offset:24080
	ds_read_u16 v1, v101 offset:23040
	s_waitcnt vmcnt(7)
	ds_read_u16 v4, v101 offset:23424
	ds_read_u16 v5, v101 offset:23552
	ds_read_u16 v7, v107 offset:23696
	ds_read_u16 v8, v101 offset:23168
	ds_read_u16 v9, v107 offset:23824
	ds_read_u16 v2, v107 offset:23952
	ds_read_u16 v3, v101 offset:23296
	s_waitcnt lgkmcnt(7)
	v_lshlrev_b32_e32 v10, 16, v1
	s_waitcnt lgkmcnt(6)
	v_lshlrev_b32_e32 v1, 16, v4
	v_lshlrev_b32_e32 v11, 16, v0
	v_sub_f32_e32 v0, v1, v11
	v_fma_f32 v0, v139, v0, v11
	v_add_f32_e32 v0, v0, v0
	v_mul_f32_e32 v0, 0x3fb8aa3b, v0
	v_exp_f32_e32 v12, v0
	s_waitcnt lgkmcnt(5)
	v_lshlrev_b32_e32 v4, 16, v5
	ds_read_u16 v5, v107 offset:24208
	s_waitcnt lgkmcnt(4)
	v_lshlrev_b32_e32 v0, 16, v8
	v_add_f32_e32 v8, 1.0, v12
	v_rcp_f32_e32 v8, v8
	v_lshlrev_b32_e32 v7, 16, v7
	s_waitcnt lgkmcnt(0)
	v_lshlrev_b32_e32 v5, 16, v5
	v_sub_f32_e32 v4, v4, v5
	v_fma_f32 v8, v8, -2.0, 1.0
	v_fma_f32 v4, v146, v4, v5
	v_cvt_pk_bf16_f32 v8, v8, s0
	v_cvt_pk_bf16_f32 v4, v4, s0
	v_lshlrev_b32_e32 v1, 16, v9
	v_sub_f32_e32 v9, v10, v7
	ds_write_b16 v101, v8 offset:18432
	ds_write_b16 v107, v4 offset:20736
	s_waitcnt vmcnt(5)
	v_fma_f32 v19, v147, v9, v7
	ds_read_u16 v4, v107 offset:24736
	ds_read_u16 v8, v107 offset:24352
	ds_read_u16 v9, v107 offset:24864
	ds_read_u16 v10, v107 offset:25008
	ds_read_u16 v12, v107 offset:24608
	s_waitcnt lgkmcnt(4)
	v_lshlrev_b32_e32 v4, 16, v4
	v_sub_f32_e32 v11, v11, v4
	v_fma_f32 v11, v139, v11, v4
	v_add_f32_e32 v11, v11, v11
	v_mul_f32_e32 v11, 0x3fb8aa3b, v11
	v_exp_f32_e32 v11, v11
	s_waitcnt lgkmcnt(3)
	v_lshlrev_b32_e32 v8, 16, v8
	s_waitcnt lgkmcnt(2)
	v_lshlrev_b32_e32 v9, 16, v9
	v_sub_f32_e32 v7, v7, v8
	v_add_f32_e32 v11, 1.0, v11
	v_rcp_f32_e32 v11, v11
	v_sub_f32_e32 v5, v5, v9
	s_waitcnt vmcnt(2)
	v_fma_f32 v43, v147, v7, v8
	v_fma_f32 v5, v146, v5, v9
	v_fma_f32 v7, v11, -2.0, 1.0
	v_cvt_pk_bf16_f32 v7, v7, s0
	v_cvt_pk_bf16_f32 v5, v5, s0
	ds_read_u16 v13, v107 offset:24480
	ds_read_u16 v18, v107 offset:33920
	ds_read_u16 v26, v107 offset:34048
	ds_write_b16 v107, v7 offset:18576
	ds_write_b16 v107, v5 offset:20880
	ds_read_u16 v5, v107 offset:25136
	ds_read_u16 v7, v107 offset:25392
	ds_read_u16 v11, v107 offset:25520
	ds_read_u16 v16, v107 offset:25664
	ds_read_u16 v17, v107 offset:26048
	ds_read_u16 v20, v107 offset:25920
	ds_read_u16 v21, v107 offset:25792
	ds_read_u16 v22, v107 offset:25264
	s_waitcnt lgkmcnt(6)
	v_lshlrev_b32_e32 v7, 16, v7
	v_sub_f32_e32 v4, v4, v7
	v_fma_f32 v4, v139, v4, v7
	v_add_f32_e32 v4, v4, v4
	v_mul_f32_e32 v4, 0x3fb8aa3b, v4
	v_exp_f32_e32 v4, v4
	s_waitcnt lgkmcnt(3)
	v_lshlrev_b32_e32 v17, 16, v17
	v_lshlrev_b32_e32 v14, 16, v13
	v_lshlrev_b32_e32 v13, 16, v11
	v_lshlrev_b32_e32 v11, 16, v2
	v_sub_f32_e32 v2, v7, v17
	v_fma_f32 v2, v139, v2, v17
	v_add_f32_e32 v2, v2, v2
	v_add_f32_e32 v4, 1.0, v4
	v_mul_f32_e32 v2, 0x3fb8aa3b, v2
	v_rcp_f32_e32 v4, v4
	v_exp_f32_e32 v7, v2
	v_lshlrev_b32_e32 v10, 16, v10
	v_lshlrev_b32_e32 v15, 16, v5
	v_fma_f32 v4, v4, -2.0, 1.0
	v_add_f32_e32 v7, 1.0, v7
	v_cvt_pk_bf16_f32 v4, v4, s0
	v_rcp_f32_e32 v7, v7
	ds_write_b16 v107, v4 offset:18720
	v_sub_f32_e32 v4, v9, v13
	v_fma_f32 v4, v146, v4, v13
	v_cvt_pk_bf16_f32 v4, v4, s0
	ds_write_b16 v107, v4 offset:21024
	v_fma_f32 v7, v7, -2.0, 1.0
	ds_read_u16 v4, v107 offset:26176
	ds_read_u16 v23, v107 offset:26320
	ds_read_u16 v24, v107 offset:26448
	ds_read_u16 v25, v107 offset:26576
	ds_read_u16 v27, v107 offset:26704
	ds_read_u16 v28, v107 offset:26832
	ds_read_u16 v29, v107 offset:26976
	ds_read_u16 v30, v107 offset:27104
	s_waitcnt vmcnt(1) lgkmcnt(7)
	v_lshlrev_b32_e32 v32, 16, v4
	v_cvt_pk_bf16_f32 v7, v7, s0
	v_sub_f32_e32 v5, v8, v10
	v_lshlrev_b32_e32 v16, 16, v16
	ds_write_b16 v107, v7 offset:18864
	v_sub_f32_e32 v7, v13, v32
	s_waitcnt vmcnt(0)
	v_fma_f32 v39, v147, v5, v10
	v_sub_f32_e32 v4, v10, v16
	v_lshlrev_b32_e32 v5, 16, v22
	v_fma_f32 v7, v146, v7, v32
	v_fma_f32 v35, v147, v4, v16
	v_lshlrev_b32_e32 v4, 16, v12
	v_lshlrev_b32_e32 v9, 16, v20
	v_lshlrev_b32_e32 v10, 16, v3
	v_mov_b32_e32 v8, v5
	v_cvt_pk_bf16_f32 v7, v7, s0
	v_pk_mov_b32 v[2:3], v[10:11], v[4:5] op_sel:[1,0]
	v_pk_add_f32 v[4:5], v[4:5], v[8:9] neg_lo:[0,1] neg_hi:[0,1]
	ds_write_b16 v107, v7 offset:21168
	s_waitcnt lgkmcnt(5)
	v_lshlrev_b32_e32 v7, 16, v27
	v_pk_fma_f32 v[4:5], v[82:83], v[4:5], v[8:9]
	v_sub_f32_e32 v8, v17, v7
	v_fma_f32 v8, v139, v8, v7
	v_add_f32_e32 v8, v8, v8
	v_mul_f32_e32 v8, 0x3fb8aa3b, v8
	v_exp_f32_e32 v8, v8
	v_lshlrev_b32_e32 v33, 16, v23
	v_pk_add_f32 v[10:11], v[10:11], v[2:3] neg_lo:[0,1] neg_hi:[0,1]
	v_sub_f32_e32 v16, v16, v33
	v_add_f32_e32 v8, 1.0, v8
	v_rcp_f32_e32 v8, v8
	v_pk_fma_f32 v[2:3], v[82:83], v[10:11], v[2:3]
	v_lshlrev_b32_e32 v10, 16, v21
	v_fma_f32 v31, v147, v16, v33
	v_fma_f32 v8, v8, -2.0, 1.0
	v_cvt_pk_bf16_f32 v8, v8, s0
	ds_write_b16 v107, v8 offset:19008
	ds_read_u16 v8, v107 offset:27360
	ds_read_u16 v16, v107 offset:27488
	ds_read_u16 v34, v107 offset:27632
	ds_read_u16 v36, v107 offset:27760
	ds_read_u16 v17, v107 offset:28016
	ds_read_u16 v20, v107 offset:28144
	ds_read_u16 v21, v107 offset:27888
	ds_read_u16 v22, v107 offset:27232
	s_waitcnt lgkmcnt(13)
	v_lshlrev_b32_e32 v12, 16, v28
	s_waitcnt lgkmcnt(7)
	v_lshlrev_b32_e32 v8, 16, v8
	v_sub_f32_e32 v7, v7, v8
	v_sub_f32_e32 v23, v32, v12
	v_fma_f32 v7, v139, v7, v8
	v_fma_f32 v23, v146, v23, v12
	v_add_f32_e32 v7, v7, v7
	v_cvt_pk_bf16_f32 v23, v23, s0
	v_mul_f32_e32 v7, 0x3fb8aa3b, v7
	ds_write_b16 v107, v23 offset:21312
	s_waitcnt lgkmcnt(4)
	v_lshlrev_b32_e32 v23, 16, v17
	v_exp_f32_e32 v7, v7
	v_sub_f32_e32 v8, v8, v23
	v_fma_f32 v8, v139, v8, v23
	v_add_f32_e32 v8, v8, v8
	v_mul_f32_e32 v8, 0x3fb8aa3b, v8
	v_add_f32_e32 v7, 1.0, v7
	v_exp_f32_e32 v8, v8
	v_rcp_f32_e32 v7, v7
	v_lshlrev_b32_e32 v16, 16, v16
	v_lshlrev_b32_e32 v11, 16, v24
	v_add_f32_e32 v8, 1.0, v8
	v_fma_f32 v7, v7, -2.0, 1.0
	v_rcp_f32_e32 v8, v8
	v_cvt_pk_bf16_f32 v7, v7, s0
	ds_write_b16 v107, v7 offset:19152
	v_sub_f32_e32 v7, v12, v16
	v_fma_f32 v7, v146, v7, v16
	v_cvt_pk_bf16_f32 v7, v7, s0
	v_fma_f32 v8, v8, -2.0, 1.0
	ds_write_b16 v107, v7 offset:21456
	s_waitcnt lgkmcnt(5)
	v_lshlrev_b32_e32 v7, 16, v20
	v_cvt_pk_bf16_f32 v8, v8, s0
	ds_write_b16 v107, v8 offset:19296
	v_sub_f32_e32 v8, v16, v7
	v_fma_f32 v8, v146, v8, v7
	v_cvt_pk_bf16_f32 v8, v8, s0
	ds_write_b16 v107, v8 offset:21600
	v_lshlrev_b32_e32 v13, 16, v25
	ds_read_u16 v8, v107 offset:28672
	ds_read_u16 v12, v107 offset:28800
	ds_read_u16 v37, v107 offset:28944
	ds_read_u16 v38, v107 offset:29072
	ds_read_u16 v24, v107 offset:29200
	ds_read_u16 v20, v107 offset:28544
	s_waitcnt lgkmcnt(5)
	v_lshlrev_b32_e32 v25, 16, v8
	s_waitcnt lgkmcnt(4)
	v_lshlrev_b32_e32 v27, 16, v12
	v_mov_b32_e32 v12, v9
	v_sub_f32_e32 v9, v23, v25
	v_fma_f32 v9, v139, v9, v25
	v_add_f32_e32 v9, v9, v9
	v_mul_f32_e32 v9, 0x3fb8aa3b, v9
	v_lshlrev_b32_e32 v17, 16, v21
	s_waitcnt lgkmcnt(0)
	v_lshlrev_b32_e32 v21, 16, v20
	v_exp_f32_e32 v20, v9
	v_lshlrev_b32_e32 v16, 16, v22
	v_mov_b32_e32 v8, v13
	v_mov_b32_e32 v9, v16
	v_pk_add_f32 v[12:13], v[12:13], v[8:9] neg_lo:[0,1] neg_hi:[0,1]
	ds_read_u16 v40, v107 offset:28288
	ds_read_u16 v41, v107 offset:28416
	v_pk_fma_f32 v[8:9], v[82:83], v[12:13], v[8:9]
	v_add_f32_e32 v12, 1.0, v20
	v_rcp_f32_e32 v22, v12
	v_mov_b32_e32 v20, v17
	v_pk_add_f32 v[12:13], v[16:17], v[20:21] neg_lo:[0,1] neg_hi:[0,1]
	v_sub_f32_e32 v7, v7, v27
	v_fma_f32 v16, v22, -2.0, 1.0
	v_cvt_pk_bf16_f32 v16, v16, s0
	ds_write_b16 v107, v16 offset:19440
	v_pk_fma_f32 v[12:13], v[82:83], v[12:13], v[20:21]
	ds_read_u16 v16, v107 offset:29328
	ds_read_u16 v20, v107 offset:29456
	ds_read_u16 v42, v107 offset:29600
	ds_read_u16 v22, v107 offset:29984
	ds_read_u16 v23, v107 offset:30112
	ds_read_u16 v48, v107 offset:29728
	ds_read_u16 v49, v107 offset:30256
	ds_read_u16 v28, v107 offset:29856
	s_waitcnt lgkmcnt(7)
	v_lshlrev_b32_e32 v16, 16, v16
	v_sub_f32_e32 v17, v25, v16
	v_fma_f32 v17, v139, v17, v16
	v_add_f32_e32 v17, v17, v17
	v_mul_f32_e32 v17, 0x3fb8aa3b, v17
	v_exp_f32_e32 v17, v17
	v_fma_f32 v7, v146, v7, v27
	v_cvt_pk_bf16_f32 v7, v7, s0
	s_waitcnt lgkmcnt(4)
	v_lshlrev_b32_e32 v22, 16, v22
	v_add_f32_e32 v17, 1.0, v17
	v_rcp_f32_e32 v25, v17
	ds_write_b16 v107, v7 offset:21744
	v_lshlrev_b32_e32 v7, 16, v20
	v_sub_f32_e32 v16, v16, v22
	v_fma_f32 v20, v25, -2.0, 1.0
	v_cvt_pk_bf16_f32 v20, v20, s0
	v_fma_f32 v16, v139, v16, v22
	v_add_f32_e32 v16, v16, v16
	ds_write_b16 v107, v20 offset:19584
	v_sub_f32_e32 v20, v27, v7
	v_mul_f32_e32 v16, 0x3fb8aa3b, v16
	v_fma_f32 v20, v146, v20, v7
	v_exp_f32_e32 v16, v16
	v_cvt_pk_bf16_f32 v20, v20, s0
	ds_write_b16 v107, v20 offset:21888
	v_lshlrev_b32_e32 v32, 16, v29
	v_lshlrev_b32_e32 v17, 16, v24
	s_waitcnt lgkmcnt(6)
	v_lshlrev_b32_e32 v20, 16, v23
	ds_read_u16 v51, v107 offset:30384
	ds_read_u16 v23, v107 offset:30640
	ds_read_u16 v24, v107 offset:30768
	ds_read_u16 v56, v107 offset:30912
	ds_read_u16 v25, v107 offset:31296
	ds_read_u16 v27, v107 offset:31168
	ds_read_u16 v59, v107 offset:31040
	ds_read_u16 v29, v107 offset:30512
	s_waitcnt lgkmcnt(6)
	v_lshlrev_b32_e32 v44, 16, v23
	v_sub_f32_e32 v22, v22, v44
	v_add_f32_e32 v16, 1.0, v16
	v_fma_f32 v22, v139, v22, v44
	v_rcp_f32_e32 v16, v16
	v_add_f32_e32 v22, v22, v22
	v_mul_f32_e32 v22, 0x3fb8aa3b, v22
	v_exp_f32_e32 v22, v22
	v_fma_f32 v16, v16, -2.0, 1.0
	v_cvt_pk_bf16_f32 v16, v16, s0
	ds_write_b16 v107, v16 offset:19728
	v_add_f32_e32 v16, 1.0, v22
	v_rcp_f32_e32 v16, v16
	v_sub_f32_e32 v7, v7, v20
	v_fma_f32 v7, v146, v7, v20
	v_cvt_pk_bf16_f32 v7, v7, s0
	v_fma_f32 v16, v16, -2.0, 1.0
	ds_write_b16 v107, v7 offset:22032
	s_waitcnt lgkmcnt(7)
	v_lshlrev_b32_e32 v7, 16, v24
	v_cvt_pk_bf16_f32 v16, v16, s0
	ds_write_b16 v107, v16 offset:19872
	v_sub_f32_e32 v16, v20, v7
	v_fma_f32 v16, v146, v16, v7
	v_cvt_pk_bf16_f32 v16, v16, s0
	ds_write_b16 v107, v16 offset:22176
	s_waitcnt lgkmcnt(7)
	v_lshlrev_b32_e32 v45, 16, v25
	ds_read_u16 v16, v107 offset:31424
	ds_read_u16 v60, v107 offset:31568
	ds_read_u16 v61, v107 offset:31696
	ds_read_u16 v46, v107 offset:31824
	ds_read_u16 v47, v107 offset:31952
	ds_read_u16 v52, v107 offset:32080
	ds_read_u16 v63, v107 offset:32224
	ds_read_u16 v94, v107 offset:32352
	s_waitcnt lgkmcnt(7)
	v_lshlrev_b32_e32 v53, 16, v16
	v_mov_b32_e32 v16, v21
	v_sub_f32_e32 v21, v44, v45
	v_fma_f32 v21, v139, v21, v45
	v_add_f32_e32 v21, v21, v21
	v_mul_f32_e32 v21, 0x3fb8aa3b, v21
	v_exp_f32_e32 v24, v21
	v_lshlrev_b32_e32 v22, 16, v28
	v_mov_b32_e32 v20, v17
	v_mov_b32_e32 v21, v22
	v_pk_add_f32 v[16:17], v[16:17], v[20:21] neg_lo:[0,1] neg_hi:[0,1]
	v_lshlrev_b32_e32 v25, 16, v27
	v_pk_fma_f32 v[16:17], v[82:83], v[16:17], v[20:21]
	v_add_f32_e32 v20, 1.0, v24
	v_rcp_f32_e32 v27, v20
	v_lshlrev_b32_e32 v23, 16, v29
	v_mov_b32_e32 v24, v23
	v_pk_add_f32 v[20:21], v[22:23], v[24:25] neg_lo:[0,1] neg_hi:[0,1]
	v_fma_f32 v22, v27, -2.0, 1.0
	v_cvt_pk_bf16_f32 v22, v22, s0
	ds_write_b16 v107, v22 offset:20016
	s_waitcnt lgkmcnt(4)
	v_lshlrev_b32_e32 v22, 16, v47
	v_sub_f32_e32 v23, v45, v22
	v_fma_f32 v23, v139, v23, v22
	v_add_f32_e32 v23, v23, v23
	v_mul_f32_e32 v23, 0x3fb8aa3b, v23
	v_exp_f32_e32 v23, v23
	v_sub_f32_e32 v7, v7, v53
	v_fma_f32 v7, v146, v7, v53
	v_cvt_pk_bf16_f32 v7, v7, s0
	ds_write_b16 v107, v7 offset:22320
	v_add_f32_e32 v7, 1.0, v23
	ds_read_u16 v27, v107 offset:32608
	v_rcp_f32_e32 v7, v7
	v_pk_fma_f32 v[20:21], v[82:83], v[20:21], v[24:25]
	s_waitcnt lgkmcnt(5)
	v_lshlrev_b32_e32 v24, 16, v52
	ds_read_u16 v28, v107 offset:32736
	ds_read_u16 v29, v107 offset:32480
	v_fma_f32 v7, v7, -2.0, 1.0
	s_waitcnt lgkmcnt(2)
	v_lshlrev_b32_e32 v27, 16, v27
	v_cvt_pk_bf16_f32 v7, v7, s0
	v_sub_f32_e32 v22, v22, v27
	v_fma_f32 v22, v139, v22, v27
	ds_write_b16 v107, v7 offset:20160
	v_sub_f32_e32 v7, v53, v24
	v_add_f32_e32 v22, v22, v22
	v_fma_f32 v7, v146, v7, v24
	v_mul_f32_e32 v22, 0x3fb8aa3b, v22
	v_cvt_pk_bf16_f32 v7, v7, s0
	v_exp_f32_e32 v22, v22
	ds_write_b16 v107, v7 offset:22464
	v_lshlrev_b32_e32 v23, 16, v46
	s_waitcnt lgkmcnt(3)
	v_lshlrev_b32_e32 v7, 16, v28
	ds_read_u16 v95, v107 offset:32880
	ds_read_u16 v155, v107 offset:33008
	ds_read_u16 v28, v107 offset:33264
	ds_read_u16 v44, v107 offset:33392
	ds_read_u16 v160, v107 offset:33536
	ds_read_u16 v161, v107 offset:33664
	ds_read_u16 v45, v107 offset:33792
	ds_read_u16 v46, v107 offset:33136
	s_waitcnt lgkmcnt(5)
	v_lshlrev_b32_e32 v28, 16, v28
	v_sub_f32_e32 v27, v27, v28
	v_add_f32_e32 v22, 1.0, v22
	v_fma_f32 v27, v139, v27, v28
	v_rcp_f32_e32 v22, v22
	v_add_f32_e32 v27, v27, v27
	v_mul_f32_e32 v27, 0x3fb8aa3b, v27
	v_exp_f32_e32 v27, v27
	v_fma_f32 v22, v22, -2.0, 1.0
	v_cvt_pk_bf16_f32 v22, v22, s0
	ds_write_b16 v107, v22 offset:20304
	v_sub_f32_e32 v22, v24, v7
	v_add_f32_e32 v24, 1.0, v27
	v_rcp_f32_e32 v24, v24
	s_waitcnt lgkmcnt(5)
	v_lshlrev_b32_e32 v44, 16, v44
	v_fma_f32 v22, v146, v22, v7
	v_sub_f32_e32 v7, v7, v44
	v_cvt_pk_bf16_f32 v22, v22, s0
	v_fma_f32 v7, v146, v7, v44
	ds_write_b16 v107, v22 offset:22608
	v_fma_f32 v22, v24, -2.0, 1.0
	v_cvt_pk_bf16_f32 v7, v7, s0
	v_cvt_pk_bf16_f32 v22, v22, s0
	ds_write_b16 v107, v7 offset:22752
	v_lshlrev_b32_e32 v7, 16, v18
	ds_write_b16 v107, v22 offset:20448
	v_mov_b32_e32 v22, v25
	v_sub_f32_e32 v25, v28, v7
	v_fmac_f32_e32 v7, v139, v25
	v_add_f32_e32 v7, v7, v7
	v_mul_f32_e32 v7, 0x3fb8aa3b, v7
	v_exp_f32_e32 v7, v7
	v_lshlrev_b32_e32 v18, 16, v26
	v_lshlrev_b32_e32 v26, 16, v29
	s_waitcnt lgkmcnt(4)
	v_lshlrev_b32_e32 v27, 16, v46
	v_add_f32_e32 v7, 1.0, v7
	v_rcp_f32_e32 v7, v7
	v_mov_b32_e32 v24, v23
	v_mov_b32_e32 v25, v26
	v_lshlrev_b32_e32 v29, 16, v45
	v_fma_f32 v7, v7, -2.0, 1.0
	v_cvt_pk_bf16_f32 v7, v7, s0
	v_pk_add_f32 v[22:23], v[22:23], v[24:25] neg_lo:[0,1] neg_hi:[0,1]
	v_mov_b32_e32 v28, v27
	ds_write_b16 v107, v7 offset:20592
	v_sub_f32_e32 v7, v44, v18
	v_add_u32_e32 v6, s26, v153
	v_pk_fma_f32 v[22:23], v[82:83], v[22:23], v[24:25]
	v_pk_add_f32 v[24:25], v[26:27], v[28:29] neg_lo:[0,1] neg_hi:[0,1]
	v_fmac_f32_e32 v18, v146, v7
	v_mov_b64_e32 v[26:27], s[86:87]
	s_movk_i32 s27, 0x3180
	v_cvt_pk_bf16_f32 v7, v18, s0
	v_mad_i64_i32 v[88:89], s[28:29], v6, s27, v[26:27]
	ds_write_b16 v107, v7 offset:22896
	v_lshl_add_u64 v[6:7], v[88:89], 0, v[72:73]
	v_cvt_pk_bf16_f32 v2, v2, v3
	v_cvt_pk_bf16_f32 v3, v4, v5
	v_lshl_add_u64 v[4:5], v[6:7], 0, v[74:75]
	s_mov_b64 s[28:29], 0x2800
	s_movk_i32 s27, 0x2000
	v_lshl_add_u64 v[6:7], v[4:5], 0, s[28:29]
	v_add_co_u32_e32 v4, vcc, s27, v4
	v_pk_fma_f32 v[24:25], v[82:83], v[24:25], v[28:29]
	s_nop 0
	v_addc_co_u32_e32 v5, vcc, 0, v5, vcc
	global_store_dwordx2 v[4:5], v[2:3], off offset:2048 nt
	v_cvt_pk_bf16_f32 v2, v8, v9
	v_cvt_pk_bf16_f32 v3, v12, v13
	global_store_dwordx2 v[6:7], v[2:3], off offset:128 nt
	v_cvt_pk_bf16_f32 v2, v16, v17
	v_cvt_pk_bf16_f32 v3, v20, v21
	global_store_dwordx2 v[6:7], v[2:3], off offset:256 nt
	v_cvt_pk_bf16_f32 v2, v22, v23
	v_cvt_pk_bf16_f32 v3, v24, v25
	global_store_dwordx2 v[6:7], v[2:3], off offset:384 nt
	s_waitcnt lgkmcnt(0)
	ds_read_b128 v[2:5], v102 offset:18432
	v_sub_f32_e32 v6, v33, v32
	v_fma_f32 v81, v147, v6, v32
	ds_read_b128 v[44:47], v102 offset:18496
	ds_read_b128 v[6:9], v108
	ds_read_b128 v[90:93], v102 offset:20736
	ds_read_b128 v[20:23], v108 offset:64
	s_waitcnt lgkmcnt(2)
	v_mfma_f32_16x16x32_bf16 v[6:9], v[2:5], v[6:9], 0
	ds_read_b128 v[156:159], v102 offset:20800
	ds_read_b128 v[52:55], v108 offset:9216
	v_lshlrev_b32_e32 v12, 16, v34
	v_sub_f32_e32 v13, v32, v12
	s_waitcnt lgkmcnt(2)
	v_mfma_f32_16x16x32_bf16 v[6:9], v[44:47], v[20:23], v[6:9]
	ds_read_b128 v[20:23], v108 offset:9280
	v_fma_f32 v62, v147, v13, v12
	v_lshlrev_b32_e32 v13, 16, v40
	s_waitcnt lgkmcnt(1)
	v_mfma_f32_16x16x32_bf16 v[52:55], v[90:93], v[52:55], 0
	v_sub_f32_e32 v12, v12, v13
	v_fma_f32 v58, v147, v12, v13
	v_lshlrev_b32_e32 v12, 16, v37
	s_waitcnt lgkmcnt(0)
	v_mfma_f32_16x16x32_bf16 v[20:23], v[156:159], v[20:23], v[52:55]
	v_sub_f32_e32 v13, v13, v12
	v_lshlrev_b32_e32 v16, 16, v42
	v_fma_f32 v57, v147, v13, v12
	v_sub_f32_e32 v12, v12, v16
	v_lshlrev_b32_e32 v17, 16, v49
	s_nop 2
	ds_write2st64_b32 v110, v6, v20 offset0:90 offset1:107
	v_add_u32_e32 v6, 0x5a00, v111
	ds_write2_b32 v6, v7, v8 offset0:68 offset1:136
	v_add_u32_e32 v6, 0x6c00, v111
	ds_write2_b32 v6, v21, v22 offset0:4 offset1:72
	ds_write_b32 v111, v9 offset:23856
	ds_write_b32 v111, v23 offset:28208
	ds_read_b128 v[6:9], v112
	ds_read_b128 v[22:25], v112 offset:64
	s_waitcnt lgkmcnt(1)
	v_mfma_f32_16x16x32_bf16 v[6:9], v[2:5], v[6:9], 0
	ds_read_b128 v[52:55], v112 offset:9216
	v_lshlrev_b32_e32 v18, 16, v95
	s_mov_b32 s27, 0xbf1b4598
	s_waitcnt lgkmcnt(1)
	v_mfma_f32_16x16x32_bf16 v[6:9], v[44:47], v[22:25], v[6:9]
	ds_read_b128 v[22:25], v112 offset:9280
	v_lshlrev_b32_e32 v13, 16, v51
	v_lshlrev_b32_e32 v51, 16, v160
	s_waitcnt lgkmcnt(1)
	v_mfma_f32_16x16x32_bf16 v[178:181], v[90:93], v[52:55], 0
	v_fma_f32 v55, v147, v12, v16
	v_sub_f32_e32 v16, v16, v17
	v_fma_f32 v54, v147, v16, v17
	s_waitcnt lgkmcnt(0)
	v_mfma_f32_16x16x32_bf16 v[22:25], v[156:159], v[22:25], v[178:181]
	ds_write_b32 v111, v6 offset:23104
	s_nop 6
	ds_write_b32 v111, v22 offset:27456
	v_add_u32_e32 v6, 0x5a00, v113
	ds_write2_b32 v6, v7, v8 offset0:68 offset1:136
	v_add_u32_e32 v6, 0x6c00, v113
	ds_write2_b32 v6, v23, v24 offset0:4 offset1:72
	ds_write_b32 v113, v9 offset:23856
	ds_write_b32 v113, v25 offset:28208
	ds_read_b128 v[6:9], v114
	ds_read_b128 v[22:25], v114 offset:64
	ds_read_b128 v[178:181], v114 offset:9216
	ds_read_b128 v[186:189], v114 offset:9280
	s_waitcnt lgkmcnt(3)
	v_mfma_f32_16x16x32_bf16 v[6:9], v[2:5], v[6:9], 0
	v_lshlrev_b32_e32 v16, 16, v56
	v_sub_f32_e32 v17, v17, v16
	v_lshlrev_b32_e32 v12, 16, v48
	s_waitcnt lgkmcnt(1)
	v_mfma_f32_16x16x32_bf16 v[178:181], v[90:93], v[178:181], 0
	v_lshlrev_b32_e32 v20, 16, v41
	v_lshlrev_b32_e32 v27, 16, v36
	v_lshlrev_b32_e32 v21, 16, v38
	v_mfma_f32_16x16x32_bf16 v[182:185], v[44:47], v[22:25], v[6:9]
	v_fma_f32 v25, v147, v17, v16
	v_add_u32_e32 v24, 0x5c00, v118
	v_lshlrev_b32_e32 v26, 16, v30
	s_waitcnt lgkmcnt(0)
	v_mfma_f32_16x16x32_bf16 v[178:181], v[156:159], v[186:189], v[178:181]
	v_lshlrev_b32_e32 v6, 16, v60
	v_sub_f32_e32 v7, v16, v6
	v_add_u32_e32 v16, 0x5a00, v115
	ds_write_b32 v111, v182 offset:23168
	s_nop 3
	ds_write_b32 v111, v178 offset:27520
	ds_write2_b32 v16, v183, v184 offset0:68 offset1:136
	v_add_u32_e32 v16, 0x6c00, v115
	ds_write2_b32 v16, v179, v180 offset0:4 offset1:72
	ds_write_b32 v115, v185 offset:23856
	ds_write_b32 v115, v181 offset:28208
	ds_read_b128 v[178:181], v116
	ds_read_b128 v[182:185], v116 offset:64
	s_waitcnt lgkmcnt(1)
	v_mfma_f32_16x16x32_bf16 v[2:5], v[2:5], v[178:181], 0
	ds_read_b128 v[178:181], v116 offset:9216
	v_fma_f32 v53, v147, v7, v6
	v_lshlrev_b32_e32 v7, 16, v63
	s_waitcnt lgkmcnt(1)
	v_mfma_f32_16x16x32_bf16 v[44:47], v[44:47], v[182:185], v[2:5]
	ds_read_b128 v[182:185], v116 offset:9280
	v_sub_f32_e32 v6, v6, v7
	v_fma_f32 v52, v147, v6, v7
	s_waitcnt lgkmcnt(1)
	v_mfma_f32_16x16x32_bf16 v[90:93], v[90:93], v[178:181], 0
	v_add_u32_e32 v5, 0x5a00, v117
	v_sub_f32_e32 v4, v7, v18
	v_add_u32_e32 v16, 0x5800, v118
	s_waitcnt lgkmcnt(0)
	v_mfma_f32_16x16x32_bf16 v[90:93], v[156:159], v[182:185], v[90:93]
	ds_write_b32 v111, v44 offset:23232
	s_nop 6
	ds_write_b32 v111, v90 offset:27584
	ds_write2_b32 v5, v45, v46 offset0:68 offset1:136
	v_add_u32_e32 v5, 0x6c00, v117
	ds_write2_b32 v5, v91, v92 offset0:4 offset1:72
	ds_write_b32 v117, v47 offset:23856
	ds_write_b32 v117, v93 offset:28208
	v_add_u32_e32 v5, 0x6a00, v118
	s_waitcnt lgkmcnt(0)
	ds_read2_b32 v[6:7], v5 offset0:64 offset1:132
	ds_read2_b32 v[16:17], v16 offset0:128 offset1:196
	ds_read2_b32 v[22:23], v24 offset0:8 offset1:76
	v_fma_f32 v4, v147, v4, v18
	v_sub_f32_e32 v18, v18, v51
	s_waitcnt lgkmcnt(2)
	v_add_f32_e32 v6, v151, v6
	v_mul_f32_e32 v6, 0xbfb8aa3b, v6
	s_waitcnt lgkmcnt(1)
	v_add_f32_e32 v16, v148, v16
	v_exp_f32_e32 v6, v6
	v_mul_f32_e32 v16, 0xbfb8aa3b, v16
	v_exp_f32_e32 v16, v16
	v_add_f32_e32 v17, v148, v17
	v_add_f32_e32 v6, 1.0, v6
	v_add_f32_e32 v7, v151, v7
	v_rcp_f32_e32 v48, v6
	v_add_f32_e32 v6, 1.0, v16
	v_mul_f32_e32 v17, 0xbfb8aa3b, v17
	v_mul_f32_e32 v7, 0xbfb8aa3b, v7
	v_rcp_f32_e32 v16, v6
	v_exp_f32_e32 v17, v17
	v_exp_f32_e32 v7, v7
	v_fmac_f32_e32 v51, v147, v18
	v_fma_f32 v47, v16, s27, 0
	v_add_f32_e32 v16, 1.0, v17
	v_add_f32_e32 v7, 1.0, v7
	v_rcp_f32_e32 v49, v7
	v_rcp_f32_e32 v7, v16
	v_add_u32_e32 v16, 0x6c00, v118
	ds_read2_b32 v[16:17], v16 offset0:72 offset1:140
	v_add_f32_e32 v18, -1.0, v49
	v_fma_f32 v95, v149, v18, 1.0
	s_waitcnt lgkmcnt(1)
	v_add_f32_e32 v18, v148, v22
	v_mul_f32_e32 v18, 0xbfb8aa3b, v18
	s_waitcnt lgkmcnt(0)
	v_add_f32_e32 v16, v151, v16
	v_mul_f32_e32 v16, 0xbfb8aa3b, v16
	v_exp_f32_e32 v16, v16
	v_add_f32_e32 v17, v151, v17
	v_mul_f32_e32 v17, 0xbfb8aa3b, v17
	v_exp_f32_e32 v17, v17
	v_add_f32_e32 v16, 1.0, v16
	v_rcp_f32_e32 v44, v16
	v_exp_f32_e32 v18, v18
	v_fmamk_f32 v92, v7, 0xbf1b4598, v47
	v_add_f32_e32 v6, -1.0, v48
	v_add_f32_e32 v16, -1.0, v44
	v_fma_f32 v46, v149, v16, 1.0
	v_add_f32_e32 v16, 1.0, v17
	v_rcp_f32_e32 v45, v16
	v_add_u32_e32 v16, 0x6e00, v118
	ds_read2_b32 v[16:17], v16 offset0:80 offset1:148
	v_add_f32_e32 v7, 1.0, v18
	v_add_f32_e32 v18, v148, v23
	v_mul_f32_e32 v18, 0xbfb8aa3b, v18
	v_rcp_f32_e32 v7, v7
	s_waitcnt lgkmcnt(0)
	v_add_f32_e32 v16, v151, v16
	v_mul_f32_e32 v16, 0xbfb8aa3b, v16
	v_exp_f32_e32 v18, v18
	ds_read2_b32 v[22:23], v24 offset0:144 offset1:212
	v_exp_f32_e32 v16, v16
	v_fmamk_f32 v178, v7, 0xbf1b4598, v92
	v_add_f32_e32 v7, 1.0, v18
	v_add_f32_e32 v18, -1.0, v45
	v_add_f32_e32 v16, 1.0, v16
	v_add_f32_e32 v17, v151, v17
	v_fma_f32 v181, v149, v18, 1.0
	s_waitcnt lgkmcnt(0)
	v_add_f32_e32 v18, v148, v22
	v_rcp_f32_e32 v40, v16
	v_mul_f32_e32 v17, 0xbfb8aa3b, v17
	v_mul_f32_e32 v18, 0xbfb8aa3b, v18
	v_exp_f32_e32 v17, v17
	v_rcp_f32_e32 v7, v7
	v_exp_f32_e32 v18, v18
	v_add_f32_e32 v16, -1.0, v40
	v_fma_f32 v42, v149, v16, 1.0
	v_add_f32_e32 v16, 1.0, v17
	v_fmamk_f32 v188, v7, 0xbf1b4598, v178
	v_add_f32_e32 v7, 1.0, v18
	v_add_f32_e32 v18, v148, v23
	v_rcp_f32_e32 v41, v16
	v_add_u32_e32 v16, 0x7000, v118
	v_mul_f32_e32 v18, 0xbfb8aa3b, v18
	ds_read2_b32 v[16:17], v16 offset0:88 offset1:156
	v_add_u32_e32 v24, 0x6000, v118
	v_rcp_f32_e32 v7, v7
	v_exp_f32_e32 v18, v18
	ds_read2_b32 v[22:23], v24 offset0:24 offset1:92
	s_waitcnt lgkmcnt(1)
	v_add_f32_e32 v16, v151, v16
	v_fmamk_f32 v192, v7, 0xbf1b4598, v188
	v_add_f32_e32 v7, 1.0, v18
	v_add_f32_e32 v18, -1.0, v41
	v_fma_f32 v159, v149, v18, 1.0
	v_mul_f32_e32 v16, 0xbfb8aa3b, v16
	s_waitcnt lgkmcnt(0)
	v_add_f32_e32 v18, v148, v22
	v_exp_f32_e32 v16, v16
	v_mul_f32_e32 v18, 0xbfb8aa3b, v18
	v_rcp_f32_e32 v7, v7
	v_exp_f32_e32 v18, v18
	v_add_f32_e32 v16, 1.0, v16
	v_add_f32_e32 v17, v151, v17
	v_rcp_f32_e32 v36, v16
	v_fmamk_f32 v193, v7, 0xbf1b4598, v192
	v_add_f32_e32 v7, 1.0, v18
	v_add_f32_e32 v18, v148, v23
	v_mul_f32_e32 v17, 0xbfb8aa3b, v17
	v_exp_f32_e32 v17, v17
	v_mul_f32_e32 v18, 0xbfb8aa3b, v18
	v_exp_f32_e32 v18, v18
	v_add_f32_e32 v16, -1.0, v36
	v_fma_f32 v38, v149, v16, 1.0
	v_add_f32_e32 v16, 1.0, v17
	v_rcp_f32_e32 v7, v7
	v_rcp_f32_e32 v37, v16
	v_add_f32_e32 v16, 1.0, v18
	v_rcp_f32_e32 v16, v16
	v_fmamk_f32 v180, v7, 0xbf1b4598, v193
	v_add_f32_e32 v7, -1.0, v37
	v_lshlrev_b32_e32 v8, 16, v59
	v_lshlrev_b32_e32 v9, 16, v61
	v_lshlrev_b32_e32 v2, 16, v94
	v_lshlrev_b32_e32 v3, 16, v155
	v_lshlrev_b32_e32 v5, 16, v161
	v_fma_f32 v6, v149, v6, 1.0
	v_fma_f32 v161, v149, v7, 1.0
	v_fmamk_f32 v179, v16, 0xbf1b4598, v180
	ds_read2_b32 v[16:17], v24 offset0:160 offset1:228
	v_add_u32_e32 v7, 0x7200, v118
	ds_read2_b32 v[22:23], v7 offset0:96 offset1:164
	v_add_u32_e32 v24, 0x6400, v118
	v_add_u32_e32 v56, 0x6800, v118
	s_waitcnt lgkmcnt(1)
	v_add_f32_e32 v7, v148, v16
	v_add_f32_e32 v16, v148, v17
	v_mul_f32_e32 v7, 0xbfb8aa3b, v7
	s_waitcnt lgkmcnt(0)
	v_add_f32_e32 v17, v151, v22
	v_mul_f32_e32 v17, 0xbfb8aa3b, v17
	v_exp_f32_e32 v7, v7
	v_exp_f32_e32 v17, v17
	v_add_f32_e32 v18, v151, v23
	v_mul_f32_e32 v16, 0xbfb8aa3b, v16
	v_add_f32_e32 v7, 1.0, v7
	v_mul_f32_e32 v18, 0xbfb8aa3b, v18
	v_add_f32_e32 v17, 1.0, v17
	v_exp_f32_e32 v16, v16
	v_rcp_f32_e32 v7, v7
	v_exp_f32_e32 v18, v18
	v_rcp_f32_e32 v32, v17
	ds_read2_b32 v[22:23], v24 offset0:40 offset1:108
	v_fmamk_f32 v160, v7, 0xbf1b4598, v179
	v_add_f32_e32 v7, 1.0, v16
	v_add_f32_e32 v16, 1.0, v18
	v_add_f32_e32 v17, -1.0, v32
	v_rcp_f32_e32 v33, v16
	v_add_u32_e32 v16, 0x7400, v118
	v_fma_f32 v34, v149, v17, 1.0
	ds_read2_b32 v[16:17], v16 offset0:104 offset1:172
	v_add_f32_e32 v18, -1.0, v33
	v_fma_f32 v157, v149, v18, 1.0
	s_waitcnt lgkmcnt(1)
	v_add_f32_e32 v18, v148, v22
	v_mul_f32_e32 v18, 0xbfb8aa3b, v18
	s_waitcnt lgkmcnt(0)
	v_add_f32_e32 v16, v151, v16
	v_mul_f32_e32 v16, 0xbfb8aa3b, v16
	v_exp_f32_e32 v16, v16
	v_add_f32_e32 v17, v151, v17
	v_mul_f32_e32 v17, 0xbfb8aa3b, v17
	v_exp_f32_e32 v17, v17
	v_add_f32_e32 v16, 1.0, v16
	v_rcp_f32_e32 v28, v16
	v_rcp_f32_e32 v7, v7
	v_exp_f32_e32 v18, v18
	ds_read2_b32 v[90:91], v56 offset0:56 offset1:124
	v_add_f32_e32 v16, -1.0, v28
	v_fma_f32 v30, v149, v16, 1.0
	v_add_f32_e32 v16, 1.0, v17
	v_rcp_f32_e32 v29, v16
	v_add_u32_e32 v16, 0x7600, v118
	ds_read2_b32 v[16:17], v16 offset0:112 offset1:180
	v_fmamk_f32 v177, v7, 0xbf1b4598, v160
	v_add_f32_e32 v7, 1.0, v18
	v_add_f32_e32 v18, v148, v23
	v_mul_f32_e32 v18, 0xbfb8aa3b, v18
	s_waitcnt lgkmcnt(0)
	v_add_f32_e32 v16, v151, v16
	v_rcp_f32_e32 v7, v7
	v_exp_f32_e32 v18, v18
	ds_read2_b32 v[22:23], v24 offset0:176 offset1:244
	v_mul_f32_e32 v16, 0xbfb8aa3b, v16
	v_exp_f32_e32 v16, v16
	v_fmamk_f32 v156, v7, 0xbf1b4598, v177
	v_add_f32_e32 v7, 1.0, v18
	v_add_f32_e32 v18, -1.0, v29
	v_fma_f32 v155, v149, v18, 1.0
	s_waitcnt lgkmcnt(0)
	v_add_f32_e32 v18, v148, v22
	v_add_f32_e32 v16, 1.0, v16
	v_add_f32_e32 v17, v151, v17
	v_mul_f32_e32 v18, 0xbfb8aa3b, v18
	v_rcp_f32_e32 v22, v16
	v_mul_f32_e32 v17, 0xbfb8aa3b, v17
	v_rcp_f32_e32 v7, v7
	v_exp_f32_e32 v18, v18
	v_exp_f32_e32 v17, v17
	v_add_f32_e32 v16, -1.0, v22
	v_fmamk_f32 v158, v7, 0xbf1b4598, v156
	v_add_f32_e32 v7, 1.0, v18
	v_add_f32_e32 v18, v148, v23
	v_fma_f32 v24, v149, v16, 1.0
	v_add_f32_e32 v16, 1.0, v17
	v_mul_f32_e32 v18, 0xbfb8aa3b, v18
	v_rcp_f32_e32 v23, v16
	v_add_u32_e32 v16, 0x7800, v118
	v_rcp_f32_e32 v7, v7
	v_exp_f32_e32 v18, v18
	ds_read2_b32 v[16:17], v16 offset0:120 offset1:188
	v_add_f32_e32 v56, v148, v91
	v_fmamk_f32 v63, v7, 0xbf1b4598, v158
	v_add_f32_e32 v7, 1.0, v18
	v_add_f32_e32 v18, -1.0, v23
	v_fma_f32 v61, v149, v18, 1.0
	s_waitcnt lgkmcnt(0)
	v_add_f32_e32 v16, v151, v16
	v_add_f32_e32 v18, v148, v90
	v_add_f32_e32 v17, v151, v17
	v_mul_f32_e32 v16, 0xbfb8aa3b, v16
	v_mul_f32_e32 v18, 0xbfb8aa3b, v18
	v_mul_f32_e32 v17, 0xbfb8aa3b, v17
	v_rcp_f32_e32 v7, v7
	v_exp_f32_e32 v16, v16
	v_exp_f32_e32 v18, v18
	v_exp_f32_e32 v17, v17
	v_mul_f32_e32 v56, 0xbfb8aa3b, v56
	v_exp_f32_e32 v56, v56
	v_add_f32_e32 v16, 1.0, v16
	v_fmamk_f32 v94, v7, 0xbf1b4598, v63
	v_add_f32_e32 v7, 1.0, v18
	v_add_f32_e32 v17, 1.0, v17
	v_rcp_f32_e32 v16, v16
	v_rcp_f32_e32 v7, v7
	v_rcp_f32_e32 v17, v17
	v_add_f32_e32 v56, 1.0, v56
	v_rcp_f32_e32 v59, v56
	v_add_f32_e32 v18, -1.0, v16
	v_fmamk_f32 v60, v7, 0xbf1b4598, v94
	v_add_f32_e32 v7, -1.0, v17
	v_fma_f32 v18, v149, v18, 1.0
	v_fma_f32 v56, v149, v7, 1.0
	v_fmamk_f32 v59, v59, 0xbf1b4598, v60
	v_mul_f32_e32 v7, 0x3fb8aa3b, v59
	v_exp_f32_e32 v7, v7
	v_lshl_add_u64 v[90:91], v[88:89], 0, v[144:145]
	s_movk_i32 s27, 0x3000
	v_add_co_u32_e32 v90, vcc, s27, v90
	s_waitcnt lgkmcnt(0)
	v_mul_f32_e32 v47, 0xbfb8aa3b, v47
	s_nop 0
	v_addc_co_u32_e32 v91, vcc, 0, v91, vcc
	global_store_dword v[90:91], v7, off nt
	v_mul_f32_e32 v90, 0xbfb8aa3b, v92
	v_exp_f32_e32 v190, v90
	v_pk_mov_b32 v[90:91], v[0:1], v[14:15] op_sel:[1,0]
	v_exp_f32_e32 v47, v47
	v_pk_add_f32 v[0:1], v[0:1], v[90:91] neg_lo:[0,1] neg_hi:[0,1]
	v_mul_f32_e32 v185, v190, v7
	v_pk_fma_f32 v[0:1], v[84:85], v[0:1], v[90:91]
	v_rcp_f32_e32 v189, v47
	v_pk_mul_f32 v[90:91], v[86:87], v[0:1]
	v_lshl_add_u64 v[182:183], v[88:89], 0, v[76:77]
	v_pk_mul_f32 v[92:93], v[90:91], v[90:91]
	v_mul_f32_e32 v19, v19, v189
	v_mov_b32_e32 v184, v92
	v_cvt_pk_bf16_f32 v19, v19, s0
	ds_write_b16 v119, v19 offset:29952
	v_mov_b32_dpp v184, v184 quad_perm:[1,0,3,2] row_mask:0xf bank_mask:0xf
	v_add_f32_e32 v92, v92, v184
	v_mov_b32_e32 v184, v92
	v_rcp_f32_e32 v19, v190
	s_cmp_eq_u32 s26, 56
	v_mov_b32_dpp v184, v184 quad_perm:[2,3,0,1] row_mask:0xf bank_mask:0xf
	v_add_f32_e32 v92, v92, v184
	v_mov_b32_e32 v184, v92
	v_mul_f32_e32 v43, v43, v19
	v_cvt_pk_bf16_f32 v43, v43, s0
	v_mov_b32_dpp v184, v184 row_half_mirror row_mask:0xf bank_mask:0xf
	v_add_f32_e32 v92, v92, v184
	v_mov_b32_e32 v184, v92
	ds_write_b16 v119, v43 offset:30096
	v_mul_f32_e32 v43, v1, v95
	v_mov_b32_dpp v184, v184 row_mirror row_mask:0xf bank_mask:0xf
	v_add_f32_e32 v92, v92, v184
	v_mov_b32_e32 v184, v93
	v_readlane_b32 s27, v92, 16
	v_readlane_b32 s30, v92, 48
	v_mov_b32_dpp v184, v184 quad_perm:[1,0,3,2] row_mask:0xf bank_mask:0xf
	v_add_f32_e32 v93, v93, v184
	v_mov_b32_e32 v184, v93
	v_readlane_b32 s28, v92, 0
	v_readlane_b32 s29, v92, 32
	v_mov_b32_dpp v184, v184 quad_perm:[2,3,0,1] row_mask:0xf bank_mask:0xf
	v_add_f32_e32 v93, v93, v184
	v_mov_b32_e32 v184, v93
	v_mov_b32_e32 v186, s27
	v_mov_b32_e32 v187, s30
	v_mov_b32_dpp v184, v184 row_half_mirror row_mask:0xf bank_mask:0xf
	v_add_f32_e32 v93, v93, v184
	v_mov_b32_e32 v184, v93
	v_pk_add_f32 v[186:187], s[28:29], v[186:187]
	v_mov_b32_e32 v1, v47
	v_mov_b32_dpp v184, v184 row_mirror row_mask:0xf bank_mask:0xf
	v_add_f32_e32 v93, v93, v184
	v_add_f32_e32 v92, v186, v187
	v_readlane_b32 s27, v93, 16
	v_readlane_b32 s30, v93, 48
	v_readlane_b32 s28, v93, 0
	v_readlane_b32 s29, v93, 32
	v_mov_b32_e32 v186, s27
	v_mov_b32_e32 v187, s30
	v_pk_add_f32 v[186:187], s[28:29], v[186:187]
	v_max_f32_e32 v92, 0x179abe15, v92
	v_add_f32_e32 v93, v186, v187
	v_max_f32_e32 v93, 0x179abe15, v93
	v_rsq_f32_e32 v92, v92
	v_rsq_f32_e32 v93, v93
	v_pk_mul_f32 v[0:1], v[0:1], v[6:7]
	v_mov_b64_e32 v[194:195], s[18:19]
	v_mov_b32_e32 v184, v1
	v_pk_mul_f32 v[90:91], v[90:91], v[92:93]
	s_nop 0
	v_pk_mul_f32 v[48:49], v[48:49], v[90:91]
	v_cvt_pk_bf16_f32 v92, -v90, s0
	v_mul_f32_e32 v6, v47, v48
	v_cvt_pk_bf16_f32 v6, v6, s0
	ds_write_b16 v101, v92 offset:23040
	ds_write_b16 v119, v6 offset:25344
	v_mul_f32_e32 v6, v47, v0
	v_cvt_pk_bf16_f32 v47, v6, s0
	v_mul_f32_e32 v6, v150, v6
	v_mul_f32_e64 v91, v189, -v91
	v_cvt_pk_bf16_f32 v6, v6, s0
	v_cvt_pk_bf16_f32 v1, v91, s0
	ds_write_b16 v119, v47 offset:27648
	ds_write_b16 v101, v6 offset:18432
	ds_write_b16 v119, v1 offset:23184
	v_mul_f32_e32 v1, v190, v49
	v_cvt_pk_bf16_f32 v1, v1, s0
	ds_write_b16 v119, v1 offset:25488
	v_mul_f32_e32 v1, v190, v43
	v_cvt_pk_bf16_f32 v6, v1, s0
	v_mul_f32_e32 v1, v150, v1
	v_cvt_pk_bf16_f32 v1, v1, s0
	ds_write_b16 v119, v6 offset:27792
	ds_write_b16 v107, v1 offset:18576
	v_mov_b32_e32 v1, v43
	v_pk_mul_f32 v[186:187], v[48:49], v[184:185]
	v_pk_mul_f32 v[0:1], v[0:1], v[184:185]
	v_pk_mov_b32 v[184:185], v[14:15], v[10:11] op_sel:[1,0]
	v_mul_f32_e32 v48, 0xbfb8aa3b, v188
	v_pk_add_f32 v[14:15], v[14:15], v[184:185] neg_lo:[0,1] neg_hi:[0,1]
	v_mul_f32_e32 v6, 0xbfb8aa3b, v178
	v_pk_fma_f32 v[14:15], v[84:85], v[14:15], v[184:185]
	v_exp_f32_e32 v178, v48
	v_pk_mul_f32 v[184:185], v[86:87], v[14:15]
	v_exp_f32_e32 v6, v6
	v_pk_mul_f32 v[188:189], v[184:185], v[184:185]
	v_mov_b32_e32 v47, v7
	v_mov_b32_e32 v48, v188
	v_rcp_f32_e32 v43, v6
	v_mul_f32_e32 v49, v178, v7
	v_mov_b32_dpp v48, v48 quad_perm:[1,0,3,2] row_mask:0xf bank_mask:0xf
	v_add_f32_e32 v48, v188, v48
	v_mov_b32_e32 v93, v48
	v_mul_f32_e32 v39, v39, v43
	v_cvt_pk_bf16_f32 v39, v39, s0
	v_mov_b32_dpp v93, v93 quad_perm:[2,3,0,1] row_mask:0xf bank_mask:0xf
	v_add_f32_e32 v48, v48, v93
	v_mov_b32_e32 v93, v48
	ds_write_b16 v119, v39 offset:30240
	v_rcp_f32_e32 v39, v178
	v_mov_b32_dpp v93, v93 row_half_mirror row_mask:0xf bank_mask:0xf
	v_add_f32_e32 v48, v48, v93
	v_mov_b32_e32 v93, v48
	v_mul_f32_e32 v35, v35, v39
	v_cvt_pk_bf16_f32 v35, v35, s0
	v_mov_b32_dpp v93, v93 row_mirror row_mask:0xf bank_mask:0xf
	v_add_f32_e32 v48, v48, v93
	ds_write_b16 v119, v35 offset:30384
	v_readlane_b32 s27, v48, 16
	v_readlane_b32 s30, v48, 48
	v_readlane_b32 s28, v48, 0
	v_readlane_b32 s29, v48, 32
	v_mov_b32_e32 v190, s27
	v_mov_b32_e32 v191, s30
	v_pk_add_f32 v[190:191], s[28:29], v[190:191]
	v_mul_f32_e32 v35, v15, v181
	v_add_f32_e32 v48, v190, v191
	v_max_f32_e32 v48, 0x179abe15, v48
	v_rsq_f32_e32 v188, v48
	v_mov_b32_e32 v48, v189
	v_mov_b32_e32 v15, v6
	v_pk_mul_f32 v[14:15], v[14:15], v[46:47]
	v_mov_b32_dpp v48, v48 quad_perm:[1,0,3,2] row_mask:0xf bank_mask:0xf
	v_add_f32_e32 v48, v189, v48
	v_mov_b32_e32 v93, v48
	s_nop 1
	v_mov_b32_dpp v93, v93 quad_perm:[2,3,0,1] row_mask:0xf bank_mask:0xf
	v_add_f32_e32 v48, v48, v93
	v_mov_b32_e32 v93, v48
	s_nop 1
	v_mov_b32_dpp v93, v93 row_half_mirror row_mask:0xf bank_mask:0xf
	v_add_f32_e32 v48, v48, v93
	v_mov_b32_e32 v93, v48
	s_nop 1
	v_mov_b32_dpp v93, v93 row_mirror row_mask:0xf bank_mask:0xf
	v_add_f32_e32 v48, v48, v93
	s_nop 0
	v_readlane_b32 s27, v48, 16
	v_readlane_b32 s30, v48, 48
	v_readlane_b32 s28, v48, 0
	v_readlane_b32 s29, v48, 32
	v_mov_b32_e32 v190, s27
	v_mov_b32_e32 v191, s30
	v_pk_add_f32 v[190:191], s[28:29], v[190:191]
	s_mov_b64 s[28:29], 0x1000
	v_add_f32_e32 v48, v190, v191
	v_max_f32_e32 v48, 0x179abe15, v48
	v_rsq_f32_e32 v189, v48
	v_mov_b32_e32 v48, v15
	s_movk_i32 s27, 0x1000
	v_pk_mul_f32 v[184:185], v[184:185], v[188:189]
	s_nop 0
	v_mul_f32_e64 v95, v19, -v184
	v_pk_mul_f32 v[44:45], v[44:45], v[184:185]
	v_cvt_pk_bf16_f32 v19, v95, s0
	ds_write_b16 v119, v19 offset:23328
	v_mul_f32_e32 v19, v6, v44
	v_cvt_pk_bf16_f32 v19, v19, s0
	v_mul_f32_e32 v6, v6, v14
	ds_write_b16 v119, v19 offset:25632
	v_cvt_pk_bf16_f32 v19, v6, s0
	v_mul_f32_e32 v6, v150, v6
	v_cvt_pk_bf16_f32 v6, v6, s0
	v_mul_f32_e64 v93, v43, -v185
	ds_write_b16 v119, v19 offset:27936
	ds_write_b16 v107, v6 offset:18720
	v_cvt_pk_bf16_f32 v6, v93, s0
	ds_write_b16 v119, v6 offset:23472
	v_mul_f32_e32 v6, v178, v45
	v_cvt_pk_bf16_f32 v6, v6, s0
	ds_write_b16 v119, v6 offset:25776
	v_mul_f32_e32 v6, v178, v35
	v_cvt_pk_bf16_f32 v15, v6, s0
	v_mul_f32_e32 v6, v150, v6
	v_cvt_pk_bf16_f32 v6, v6, s0
	ds_write_b16 v119, v15 offset:28080
	ds_write_b16 v107, v6 offset:18864
	v_mul_f32_e32 v6, 0xbfb8aa3b, v192
	v_mov_b32_e32 v15, v35
	v_exp_f32_e32 v6, v6
	v_pk_mul_f32 v[46:47], v[44:45], v[48:49]
	v_pk_mul_f32 v[14:15], v[14:15], v[48:49]
	v_cvt_pk_bf16_f32 v45, v46, v47
	v_cvt_pk_bf16_f32 v47, v14, v15
	v_lshl_add_u64 v[14:15], v[182:183], 0, v[78:79]
	v_cvt_pk_bf16_f32 v46, v0, v1
	v_lshl_add_u64 v[0:1], v[14:15], 0, s[28:29]
	v_add_co_u32_e32 v14, vcc, s27, v14
	v_cvt_pk_bf16_f32 v44, v186, v187
	s_nop 0
	v_addc_co_u32_e32 v15, vcc, 0, v15, vcc
	v_rcp_f32_e32 v19, v6
	global_store_dwordx4 v[14:15], v[44:47], off nt
	v_mul_f32_e32 v14, 0xbfb8aa3b, v193
	v_exp_f32_e32 v35, v14
	v_pk_mov_b32 v[44:45], v[10:11], v[26:27] op_sel:[1,0]
	v_mul_f32_e32 v14, v31, v19
	v_pk_add_f32 v[10:11], v[10:11], v[44:45] neg_lo:[0,1] neg_hi:[0,1]
	v_cvt_pk_bf16_f32 v14, v14, s0
	v_pk_fma_f32 v[10:11], v[84:85], v[10:11], v[44:45]
	ds_write_b16 v119, v14 offset:30528
	v_pk_mul_f32 v[44:45], v[86:87], v[10:11]
	v_rcp_f32_e32 v31, v35
	v_pk_mul_f32 v[46:47], v[44:45], v[44:45]
	v_mov_b32_e32 v43, v7
	v_mov_b32_e32 v14, v46
	v_mul_f32_e32 v15, v35, v7
	s_cselect_b64 vcc, -1, 0
	v_mov_b32_dpp v14, v14 quad_perm:[1,0,3,2] row_mask:0xf bank_mask:0xf
	v_add_f32_e32 v14, v46, v14
	v_mov_b32_e32 v46, v14
	s_nop 1
	v_mov_b32_dpp v46, v46 quad_perm:[2,3,0,1] row_mask:0xf bank_mask:0xf
	v_add_f32_e32 v14, v14, v46
	v_mov_b32_e32 v46, v14
	s_nop 1
	v_mov_b32_dpp v46, v46 row_half_mirror row_mask:0xf bank_mask:0xf
	v_add_f32_e32 v14, v14, v46
	v_mov_b32_e32 v46, v14
	s_nop 1
	v_mov_b32_dpp v46, v46 row_mirror row_mask:0xf bank_mask:0xf
	v_add_f32_e32 v14, v14, v46
	s_nop 0
	v_readlane_b32 s27, v14, 16
	v_readlane_b32 s30, v14, 48
	v_readlane_b32 s28, v14, 0
	v_readlane_b32 s29, v14, 32
	v_mov_b32_e32 v48, s27
	v_mov_b32_e32 v49, s30
	v_pk_add_f32 v[48:49], s[28:29], v[48:49]
	s_nop 0
	v_add_f32_e32 v14, v48, v49
	v_max_f32_e32 v14, 0x179abe15, v14
	v_rsq_f32_e32 v46, v14
	v_mov_b32_e32 v14, v47
	s_nop 1
	v_mov_b32_dpp v14, v14 quad_perm:[1,0,3,2] row_mask:0xf bank_mask:0xf
	v_add_f32_e32 v14, v47, v14
	v_mov_b32_e32 v47, v14
	s_nop 1
	v_mov_b32_dpp v47, v47 quad_perm:[2,3,0,1] row_mask:0xf bank_mask:0xf
	v_add_f32_e32 v14, v14, v47
	v_mov_b32_e32 v47, v14
	s_nop 1
	v_mov_b32_dpp v47, v47 row_half_mirror row_mask:0xf bank_mask:0xf
	v_add_f32_e32 v14, v14, v47
	v_mov_b32_e32 v47, v14
	s_nop 1
	v_mov_b32_dpp v47, v47 row_mirror row_mask:0xf bank_mask:0xf
	v_add_f32_e32 v14, v14, v47
	s_nop 0
	v_readlane_b32 s27, v14, 16
	v_readlane_b32 s30, v14, 48
	v_readlane_b32 s28, v14, 0
	v_readlane_b32 s29, v14, 32
	v_mov_b32_e32 v48, s27
	v_mov_b32_e32 v49, s30
	v_pk_add_f32 v[48:49], s[28:29], v[48:49]
	s_nop 0
	v_add_f32_e32 v14, v48, v49
	v_max_f32_e32 v14, 0x179abe15, v14
	v_rsq_f32_e32 v47, v14
	v_mul_f32_e32 v14, v81, v31
	v_cvt_pk_bf16_f32 v14, v14, s0
	ds_write_b16 v119, v14 offset:30672
	v_pk_mul_f32 v[44:45], v[44:45], v[46:47]
	v_mul_f32_e32 v46, v11, v159
	v_mul_f32_e64 v178, v39, -v44
	v_pk_mul_f32 v[40:41], v[40:41], v[44:45]
	v_mov_b32_e32 v11, v6
	v_cvt_pk_bf16_f32 v14, v178, s0
	v_pk_mul_f32 v[10:11], v[10:11], v[42:43]
	ds_write_b16 v119, v14 offset:23616
	v_mul_f32_e32 v14, v6, v40
	v_cvt_pk_bf16_f32 v14, v14, s0
	v_mul_f32_e32 v6, v6, v10
	ds_write_b16 v119, v14 offset:25920
	v_cvt_pk_bf16_f32 v14, v6, s0
	v_mul_f32_e32 v6, v150, v6
	v_cvt_pk_bf16_f32 v6, v6, s0
	v_mul_f32_e64 v159, v19, -v45
	ds_write_b16 v119, v14 offset:28224
	ds_write_b16 v107, v6 offset:19008
	v_cvt_pk_bf16_f32 v6, v159, s0
	ds_write_b16 v119, v6 offset:23760
	v_mul_f32_e32 v6, v35, v41
	v_cvt_pk_bf16_f32 v6, v6, s0
	ds_write_b16 v119, v6 offset:26064
	v_mul_f32_e32 v6, v35, v46
	v_mov_b32_e32 v14, v11
	v_cvt_pk_bf16_f32 v11, v6, s0
	ds_write_b16 v119, v11 offset:28368
	v_mul_f32_e32 v11, 0xbfb8aa3b, v180
	v_exp_f32_e32 v19, v11
	v_mul_f32_e32 v6, v150, v6
	v_cvt_pk_bf16_f32 v6, v6, s0
	ds_write_b16 v107, v6 offset:19152
	v_rcp_f32_e32 v6, v19
	v_pk_mul_f32 v[42:43], v[40:41], v[14:15]
	v_pk_mov_b32 v[40:41], v[26:27], v[20:21] op_sel:[1,0]
	v_mov_b32_e32 v11, v46
	v_pk_add_f32 v[26:27], v[26:27], v[40:41] neg_lo:[0,1] neg_hi:[0,1]
	v_pk_mul_f32 v[10:11], v[10:11], v[14:15]
	v_mul_f32_e32 v14, 0xbfb8aa3b, v179
	v_pk_fma_f32 v[26:27], v[84:85], v[26:27], v[40:41]
	v_exp_f32_e32 v35, v14
	v_mul_f32_e32 v14, v62, v6
	v_pk_mul_f32 v[40:41], v[86:87], v[26:27]
	v_cvt_pk_bf16_f32 v14, v14, s0
	v_pk_mul_f32 v[44:45], v[40:41], v[40:41]
	ds_write_b16 v119, v14 offset:30816
	v_mov_b32_e32 v14, v44
	v_rcp_f32_e32 v48, v35
	v_mov_b32_e32 v39, v7
	v_mov_b32_dpp v14, v14 quad_perm:[1,0,3,2] row_mask:0xf bank_mask:0xf
	v_add_f32_e32 v14, v44, v14
	v_mov_b32_e32 v44, v14
	v_mul_f32_e32 v15, v35, v7
	s_nop 0
	v_mov_b32_dpp v44, v44 quad_perm:[2,3,0,1] row_mask:0xf bank_mask:0xf
	v_add_f32_e32 v14, v14, v44
	v_mov_b32_e32 v44, v14
	s_nop 1
	v_mov_b32_dpp v44, v44 row_half_mirror row_mask:0xf bank_mask:0xf
	v_add_f32_e32 v14, v14, v44
	v_mov_b32_e32 v44, v14
	s_nop 1
	v_mov_b32_dpp v44, v44 row_mirror row_mask:0xf bank_mask:0xf
	v_add_f32_e32 v14, v14, v44
	s_nop 0
	v_readlane_b32 s27, v14, 16
	v_readlane_b32 s30, v14, 48
	v_readlane_b32 s28, v14, 0
	v_readlane_b32 s29, v14, 32
	v_mov_b32_e32 v46, s27
	v_mov_b32_e32 v47, s30
	v_pk_add_f32 v[46:47], s[28:29], v[46:47]
	s_nop 0
	v_add_f32_e32 v14, v46, v47
	v_max_f32_e32 v14, 0x179abe15, v14
	v_rsq_f32_e32 v44, v14
	v_mov_b32_e32 v14, v45
	s_nop 1
	v_mov_b32_dpp v14, v14 quad_perm:[1,0,3,2] row_mask:0xf bank_mask:0xf
	v_add_f32_e32 v14, v45, v14
	v_mov_b32_e32 v45, v14
	s_nop 1
	v_mov_b32_dpp v45, v45 quad_perm:[2,3,0,1] row_mask:0xf bank_mask:0xf
	v_add_f32_e32 v14, v14, v45
	v_mov_b32_e32 v45, v14
	s_nop 1
	v_mov_b32_dpp v45, v45 row_half_mirror row_mask:0xf bank_mask:0xf
	v_add_f32_e32 v14, v14, v45
	v_mov_b32_e32 v45, v14
	s_nop 1
	v_mov_b32_dpp v45, v45 row_mirror row_mask:0xf bank_mask:0xf
	v_add_f32_e32 v14, v14, v45
	s_nop 0
	v_readlane_b32 s27, v14, 16
	v_readlane_b32 s30, v14, 48
	v_readlane_b32 s28, v14, 0
	v_readlane_b32 s29, v14, 32
	v_mov_b32_e32 v46, s27
	v_mov_b32_e32 v47, s30
	v_pk_add_f32 v[46:47], s[28:29], v[46:47]
	s_nop 0
	v_add_f32_e32 v14, v46, v47
	v_max_f32_e32 v14, 0x179abe15, v14
	v_rsq_f32_e32 v45, v14
	v_mul_f32_e32 v14, v58, v48
	v_cvt_pk_bf16_f32 v14, v14, s0
	ds_write_b16 v119, v14 offset:30960
	v_pk_mul_f32 v[40:41], v[40:41], v[44:45]
	v_mul_f32_e32 v44, v27, v161
	v_mul_f32_e64 v180, v31, -v40
	v_pk_mul_f32 v[36:37], v[36:37], v[40:41]
	v_cvt_pk_bf16_f32 v14, v180, s0
	v_mov_b32_e32 v27, v19
	ds_write_b16 v119, v14 offset:23904
	v_mul_f32_e32 v14, v19, v36
	v_pk_mul_f32 v[26:27], v[26:27], v[38:39]
	v_cvt_pk_bf16_f32 v14, v14, s0
	ds_write_b16 v119, v14 offset:26208
	v_mul_f32_e32 v14, v19, v26
	v_cvt_pk_bf16_f32 v19, v14, s0
	v_mul_f32_e32 v14, v150, v14
	v_mul_f32_e64 v161, v6, -v41
	v_cvt_pk_bf16_f32 v14, v14, s0
	v_cvt_pk_bf16_f32 v6, v161, s0
	ds_write_b16 v119, v19 offset:28512
	ds_write_b16 v107, v14 offset:19296
	ds_write_b16 v119, v6 offset:24048
	v_mul_f32_e32 v6, v35, v37
	v_cvt_pk_bf16_f32 v6, v6, s0
	ds_write_b16 v119, v6 offset:26352
	v_mul_f32_e32 v6, v35, v44
	v_cvt_pk_bf16_f32 v19, v6, s0
	v_mul_f32_e32 v6, v150, v6
	v_cvt_pk_bf16_f32 v6, v6, s0
	ds_write_b16 v119, v19 offset:28656
	ds_write_b16 v107, v6 offset:19440
	v_mul_f32_e32 v6, 0xbfb8aa3b, v160
	v_exp_f32_e32 v6, v6
	v_mov_b32_e32 v14, v27
	v_mov_b32_e32 v27, v44
	v_pk_mul_f32 v[38:39], v[36:37], v[14:15]
	v_pk_mul_f32 v[14:15], v[26:27], v[14:15]
	v_rcp_f32_e32 v19, v6
	v_cvt_pk_bf16_f32 v37, v38, v39
	v_cvt_pk_bf16_f32 v39, v14, v15
	v_pk_mov_b32 v[14:15], v[20:21], v[12:13] op_sel:[1,0]
	v_cvt_pk_bf16_f32 v38, v10, v11
	v_pk_add_f32 v[20:21], v[20:21], v[14:15] neg_lo:[0,1] neg_hi:[0,1]
	v_mul_f32_e32 v10, 0xbfb8aa3b, v177
	v_pk_fma_f32 v[14:15], v[84:85], v[20:21], v[14:15]
	v_exp_f32_e32 v31, v10
	v_mul_f32_e32 v10, v57, v19
	v_pk_mul_f32 v[20:21], v[86:87], v[14:15]
	v_cvt_pk_bf16_f32 v10, v10, s0
	v_pk_mul_f32 v[26:27], v[20:21], v[20:21]
	ds_write_b16 v119, v10 offset:31104
	v_mov_b32_e32 v10, v26
	v_cvt_pk_bf16_f32 v36, v42, v43
	global_store_dwordx4 v[0:1], v[36:39], off offset:256 nt
	v_mov_b32_dpp v10, v10 quad_perm:[1,0,3,2] row_mask:0xf bank_mask:0xf
	v_add_f32_e32 v10, v26, v10
	v_mov_b32_e32 v26, v10
	v_rcp_f32_e32 v38, v31
	v_mov_b32_e32 v35, v7
	v_mov_b32_dpp v26, v26 quad_perm:[2,3,0,1] row_mask:0xf bank_mask:0xf
	v_add_f32_e32 v10, v10, v26
	v_mov_b32_e32 v26, v10
	v_mul_f32_e32 v11, v31, v7
	s_nop 0
	v_mov_b32_dpp v26, v26 row_half_mirror row_mask:0xf bank_mask:0xf
	v_add_f32_e32 v10, v10, v26
	v_mov_b32_e32 v26, v10
	s_nop 1
	v_mov_b32_dpp v26, v26 row_mirror row_mask:0xf bank_mask:0xf
	v_add_f32_e32 v10, v10, v26
	s_nop 0
	v_readlane_b32 s27, v10, 16
	v_readlane_b32 s30, v10, 48
	v_readlane_b32 s28, v10, 0
	v_readlane_b32 s29, v10, 32
	v_mov_b32_e32 v36, s27
	v_mov_b32_e32 v37, s30
	v_pk_add_f32 v[36:37], s[28:29], v[36:37]
	s_nop 0
	v_add_f32_e32 v10, v36, v37
	v_max_f32_e32 v10, 0x179abe15, v10
	v_rsq_f32_e32 v26, v10
	v_mov_b32_e32 v10, v27
	s_nop 1
	v_mov_b32_dpp v10, v10 quad_perm:[1,0,3,2] row_mask:0xf bank_mask:0xf
	v_add_f32_e32 v10, v27, v10
	v_mov_b32_e32 v27, v10
	s_nop 1
	v_mov_b32_dpp v27, v27 quad_perm:[2,3,0,1] row_mask:0xf bank_mask:0xf
	v_add_f32_e32 v10, v10, v27
	v_mov_b32_e32 v27, v10
	s_nop 1
	v_mov_b32_dpp v27, v27 row_half_mirror row_mask:0xf bank_mask:0xf
	v_add_f32_e32 v10, v10, v27
	v_mov_b32_e32 v27, v10
	s_nop 1
	v_mov_b32_dpp v27, v27 row_mirror row_mask:0xf bank_mask:0xf
	v_add_f32_e32 v10, v10, v27
	s_nop 0
	v_readlane_b32 s27, v10, 16
	v_readlane_b32 s30, v10, 48
	v_readlane_b32 s28, v10, 0
	v_readlane_b32 s29, v10, 32
	v_mov_b32_e32 v36, s27
	v_mov_b32_e32 v37, s30
	v_pk_add_f32 v[36:37], s[28:29], v[36:37]
	s_nop 0
	v_add_f32_e32 v10, v36, v37
	v_max_f32_e32 v10, 0x179abe15, v10
	v_rsq_f32_e32 v27, v10
	v_mul_f32_e32 v10, v55, v38
	v_cvt_pk_bf16_f32 v10, v10, s0
	ds_write_b16 v119, v10 offset:31248
	v_pk_mul_f32 v[20:21], v[20:21], v[26:27]
	v_mul_f32_e32 v36, v15, v157
	v_mul_f32_e64 v181, v48, -v20
	v_pk_mul_f32 v[26:27], v[32:33], v[20:21]
	v_mov_b32_e32 v15, v6
	v_cvt_pk_bf16_f32 v10, v181, s0
	v_pk_mul_f32 v[14:15], v[14:15], v[34:35]
	ds_write_b16 v119, v10 offset:24192
	v_mul_f32_e32 v10, v6, v26
	v_cvt_pk_bf16_f32 v10, v10, s0
	v_mul_f32_e32 v6, v6, v14
	ds_write_b16 v119, v10 offset:26496
	v_cvt_pk_bf16_f32 v10, v6, s0
	v_mul_f32_e32 v6, v150, v6
	v_cvt_pk_bf16_f32 v6, v6, s0
	v_mul_f32_e64 v177, v19, -v21
	ds_write_b16 v119, v10 offset:28800
	ds_write_b16 v107, v6 offset:19584
	v_cvt_pk_bf16_f32 v6, v177, s0
	ds_write_b16 v119, v6 offset:24336
	v_mul_f32_e32 v6, v31, v27
	v_cvt_pk_bf16_f32 v6, v6, s0
	ds_write_b16 v119, v6 offset:26640
	v_mul_f32_e32 v6, v31, v36
	v_mov_b32_e32 v10, v15
	v_cvt_pk_bf16_f32 v15, v6, s0
	ds_write_b16 v119, v15 offset:28944
	v_mul_f32_e32 v15, 0xbfb8aa3b, v156
	v_exp_f32_e32 v19, v15
	v_mul_f32_e32 v6, v150, v6
	v_cvt_pk_bf16_f32 v6, v6, s0
	ds_write_b16 v107, v6 offset:19728
	v_rcp_f32_e32 v6, v19
	v_pk_mov_b32 v[20:21], v[12:13], v[8:9] op_sel:[1,0]
	v_mov_b32_e32 v15, v36
	v_pk_add_f32 v[12:13], v[12:13], v[20:21] neg_lo:[0,1] neg_hi:[0,1]
	v_pk_mul_f32 v[32:33], v[26:27], v[10:11]
	v_pk_mul_f32 v[14:15], v[14:15], v[10:11]
	v_mul_f32_e32 v10, 0xbfb8aa3b, v158
	v_pk_fma_f32 v[12:13], v[84:85], v[12:13], v[20:21]
	v_exp_f32_e32 v36, v10
	v_mul_f32_e32 v10, v54, v6
	v_pk_mul_f32 v[20:21], v[86:87], v[12:13]
	v_cvt_pk_bf16_f32 v10, v10, s0
	v_pk_mul_f32 v[26:27], v[20:21], v[20:21]
	ds_write_b16 v119, v10 offset:31392
	v_mov_b32_e32 v10, v26
	v_rcp_f32_e32 v37, v36
	v_mov_b32_e32 v31, v7
	v_mov_b32_dpp v10, v10 quad_perm:[1,0,3,2] row_mask:0xf bank_mask:0xf
	v_add_f32_e32 v10, v26, v10
	v_mov_b32_e32 v26, v10
	v_mul_f32_e32 v11, v36, v7
	s_nop 0
	v_mov_b32_dpp v26, v26 quad_perm:[2,3,0,1] row_mask:0xf bank_mask:0xf
	v_add_f32_e32 v10, v10, v26
	v_mov_b32_e32 v26, v10
	s_nop 1
	v_mov_b32_dpp v26, v26 row_half_mirror row_mask:0xf bank_mask:0xf
	v_add_f32_e32 v10, v10, v26
	v_mov_b32_e32 v26, v10
	s_nop 1
	v_mov_b32_dpp v26, v26 row_mirror row_mask:0xf bank_mask:0xf
	v_add_f32_e32 v10, v10, v26
	s_nop 0
	v_readlane_b32 s27, v10, 16
	v_readlane_b32 s30, v10, 48
	v_readlane_b32 s28, v10, 0
	v_readlane_b32 s29, v10, 32
	v_mov_b32_e32 v34, s27
	v_mov_b32_e32 v35, s30
	v_pk_add_f32 v[34:35], s[28:29], v[34:35]
	s_nop 0
	v_add_f32_e32 v10, v34, v35
	v_max_f32_e32 v10, 0x179abe15, v10
	v_rsq_f32_e32 v26, v10
	v_mov_b32_e32 v10, v27
	s_nop 1
	v_mov_b32_dpp v10, v10 quad_perm:[1,0,3,2] row_mask:0xf bank_mask:0xf
	v_add_f32_e32 v10, v27, v10
	v_mov_b32_e32 v27, v10
	s_nop 1
	v_mov_b32_dpp v27, v27 quad_perm:[2,3,0,1] row_mask:0xf bank_mask:0xf
	v_add_f32_e32 v10, v10, v27
	v_mov_b32_e32 v27, v10
	s_nop 1
	v_mov_b32_dpp v27, v27 row_half_mirror row_mask:0xf bank_mask:0xf
	v_add_f32_e32 v10, v10, v27
	v_mov_b32_e32 v27, v10
	s_nop 1
	v_mov_b32_dpp v27, v27 row_mirror row_mask:0xf bank_mask:0xf
	v_add_f32_e32 v10, v10, v27
	s_nop 0
	v_readlane_b32 s27, v10, 16
	v_readlane_b32 s30, v10, 48
	v_readlane_b32 s28, v10, 0
	v_readlane_b32 s29, v10, 32
	v_mov_b32_e32 v34, s27
	v_mov_b32_e32 v35, s30
	v_pk_add_f32 v[34:35], s[28:29], v[34:35]
	s_nop 0
	v_add_f32_e32 v10, v34, v35
	v_max_f32_e32 v10, 0x179abe15, v10
	v_rsq_f32_e32 v27, v10
	v_mul_f32_e32 v10, v25, v37
	v_cvt_pk_bf16_f32 v10, v10, s0
	ds_write_b16 v119, v10 offset:31536
	v_pk_mul_f32 v[20:21], v[20:21], v[26:27]
	v_mul_f32_e32 v25, v13, v155
	v_mul_f32_e64 v179, v38, -v20
	v_pk_mul_f32 v[26:27], v[28:29], v[20:21]
	v_cvt_pk_bf16_f32 v10, v179, s0
	v_mov_b32_e32 v13, v19
	ds_write_b16 v119, v10 offset:24480
	v_mul_f32_e32 v10, v19, v26
	v_pk_mul_f32 v[12:13], v[12:13], v[30:31]
	v_cvt_pk_bf16_f32 v10, v10, s0
	ds_write_b16 v119, v10 offset:26784
	v_mul_f32_e32 v10, v19, v12
	v_cvt_pk_bf16_f32 v19, v10, s0
	v_mul_f32_e32 v10, v150, v10
	v_mul_f32_e64 v158, v6, -v21
	v_cvt_pk_bf16_f32 v10, v10, s0
	v_cvt_pk_bf16_f32 v6, v158, s0
	ds_write_b16 v119, v19 offset:29088
	ds_write_b16 v107, v10 offset:19872
	ds_write_b16 v119, v6 offset:24624
	v_mul_f32_e32 v6, v36, v27
	v_cvt_pk_bf16_f32 v6, v6, s0
	ds_write_b16 v119, v6 offset:26928
	v_mul_f32_e32 v6, v36, v25
	v_mov_b32_e32 v10, v13
	v_cvt_pk_bf16_f32 v13, v6, s0
	v_mul_f32_e32 v6, v150, v6
	v_cvt_pk_bf16_f32 v6, v6, s0
	ds_write_b16 v119, v13 offset:29232
	ds_write_b16 v107, v6 offset:20016
	v_mul_f32_e32 v6, 0xbfb8aa3b, v63
	v_exp_f32_e32 v6, v6
	v_mov_b32_e32 v13, v25
	v_pk_mul_f32 v[28:29], v[26:27], v[10:11]
	v_pk_mul_f32 v[20:21], v[12:13], v[10:11]
	v_cvt_pk_bf16_f32 v10, v32, v33
	v_cvt_pk_bf16_f32 v11, v28, v29
	v_cvt_pk_bf16_f32 v12, v14, v15
	v_cvt_pk_bf16_f32 v13, v20, v21
	v_rcp_f32_e32 v19, v6
	global_store_dwordx4 v[0:1], v[10:13], off offset:512 nt
	v_mov_b32_e32 v25, v7
	v_add_u32_e32 v155, 0x80, v50
	v_pk_mov_b32 v[12:13], v[8:9], v[2:3] op_sel:[1,0]
	v_mul_f32_e32 v10, 0xbfb8aa3b, v94
	v_pk_add_f32 v[8:9], v[8:9], v[12:13] neg_lo:[0,1] neg_hi:[0,1]
	v_exp_f32_e32 v26, v10
	v_pk_fma_f32 v[8:9], v[84:85], v[8:9], v[12:13]
	v_mul_f32_e32 v10, v53, v19
	v_pk_mul_f32 v[12:13], v[86:87], v[8:9]
	v_cvt_pk_bf16_f32 v10, v10, s0
	v_pk_mul_f32 v[14:15], v[12:13], v[12:13]
	ds_write_b16 v119, v10 offset:31680
	v_mov_b32_e32 v10, v14
	v_rcp_f32_e32 v27, v26
	v_mul_f32_e32 v28, v9, v61
	v_mov_b32_dpp v10, v10 quad_perm:[1,0,3,2] row_mask:0xf bank_mask:0xf
	v_add_f32_e32 v10, v14, v10
	v_mov_b32_e32 v14, v10
	v_mov_b32_e32 v9, v6
	v_pk_mul_f32 v[8:9], v[8:9], v[24:25]
	v_mov_b32_dpp v14, v14 quad_perm:[2,3,0,1] row_mask:0xf bank_mask:0xf
	v_add_f32_e32 v10, v10, v14
	v_mov_b32_e32 v14, v10
	v_mul_f32_e32 v11, v26, v7
	s_nop 0
	v_mov_b32_dpp v14, v14 row_half_mirror row_mask:0xf bank_mask:0xf
	v_add_f32_e32 v10, v10, v14
	v_mov_b32_e32 v14, v10
	s_nop 1
	v_mov_b32_dpp v14, v14 row_mirror row_mask:0xf bank_mask:0xf
	v_add_f32_e32 v10, v10, v14
	s_nop 0
	v_readlane_b32 s27, v10, 16
	v_readlane_b32 s30, v10, 48
	v_readlane_b32 s28, v10, 0
	v_readlane_b32 s29, v10, 32
	v_mov_b32_e32 v20, s27
	v_mov_b32_e32 v21, s30
	v_pk_add_f32 v[20:21], s[28:29], v[20:21]
	s_nop 0
	v_add_f32_e32 v10, v20, v21
	v_max_f32_e32 v10, 0x179abe15, v10
	v_rsq_f32_e32 v14, v10
	v_mov_b32_e32 v10, v15
	s_nop 1
	v_mov_b32_dpp v10, v10 quad_perm:[1,0,3,2] row_mask:0xf bank_mask:0xf
	v_add_f32_e32 v10, v15, v10
	v_mov_b32_e32 v15, v10
	s_nop 1
	v_mov_b32_dpp v15, v15 quad_perm:[2,3,0,1] row_mask:0xf bank_mask:0xf
	v_add_f32_e32 v10, v10, v15
	v_mov_b32_e32 v15, v10
	s_nop 1
	v_mov_b32_dpp v15, v15 row_half_mirror row_mask:0xf bank_mask:0xf
	v_add_f32_e32 v10, v10, v15
	v_mov_b32_e32 v15, v10
	s_nop 1
	v_mov_b32_dpp v15, v15 row_mirror row_mask:0xf bank_mask:0xf
	v_add_f32_e32 v10, v10, v15
	s_nop 0
	v_readlane_b32 s27, v10, 16
	v_readlane_b32 s30, v10, 48
	v_readlane_b32 s28, v10, 0
	v_readlane_b32 s29, v10, 32
	v_mov_b32_e32 v20, s27
	v_mov_b32_e32 v21, s30
	v_pk_add_f32 v[20:21], s[28:29], v[20:21]
	s_nop 0
	v_add_f32_e32 v10, v20, v21
	v_max_f32_e32 v10, 0x179abe15, v10
	v_rsq_f32_e32 v15, v10
	v_mul_f32_e32 v10, v52, v27
	v_cvt_pk_bf16_f32 v10, v10, s0
	ds_write_b16 v119, v10 offset:31824
	v_pk_mul_f32 v[12:13], v[12:13], v[14:15]
	s_nop 0
	v_mul_f32_e64 v160, v37, -v12
	v_pk_mul_f32 v[14:15], v[22:23], v[12:13]
	v_cvt_pk_bf16_f32 v10, v160, s0
	ds_write_b16 v119, v10 offset:24768
	v_mul_f32_e32 v10, v6, v14
	v_cvt_pk_bf16_f32 v10, v10, s0
	v_mul_f32_e32 v6, v6, v8
	ds_write_b16 v119, v10 offset:27072
	v_cvt_pk_bf16_f32 v10, v6, s0
	v_mul_f32_e32 v6, v150, v6
	v_cvt_pk_bf16_f32 v6, v6, s0
	v_mul_f32_e64 v94, v19, -v13
	ds_write_b16 v119, v10 offset:29376
	ds_write_b16 v107, v6 offset:20160
	v_cvt_pk_bf16_f32 v6, v94, s0
	ds_write_b16 v119, v6 offset:24912
	v_mul_f32_e32 v6, v26, v15
	v_cvt_pk_bf16_f32 v6, v6, s0
	ds_write_b16 v119, v6 offset:27216
	v_mul_f32_e32 v6, v26, v28
	v_mov_b32_e32 v10, v9
	v_cvt_pk_bf16_f32 v9, v6, s0
	ds_write_b16 v119, v9 offset:29520
	v_mul_f32_e32 v9, 0xbfb8aa3b, v60
	v_pk_mul_f32 v[20:21], v[14:15], v[10:11]
	v_exp_f32_e32 v14, v9
	v_mul_f32_e32 v6, v150, v6
	v_cvt_pk_bf16_f32 v6, v6, s0
	ds_write_b16 v107, v6 offset:20304
	v_rcp_f32_e32 v22, v14
	v_mov_b32_e32 v9, v28
	v_pk_mul_f32 v[8:9], v[8:9], v[10:11]
	v_mul_f32_e32 v6, 0xbfb8aa3b, v59
	v_mul_f32_e32 v4, v4, v22
	v_cvt_pk_bf16_f32 v4, v4, s0
	ds_write_b16 v119, v4 offset:31968
	v_mov_b32_e32 v4, v3
	v_pk_add_f32 v[2:3], v[2:3], v[4:5] neg_lo:[0,1] neg_hi:[0,1]
	v_exp_f32_e32 v23, v6
	v_pk_fma_f32 v[2:3], v[84:85], v[2:3], v[4:5]
	v_mov_b32_e32 v19, v7
	v_pk_mul_f32 v[4:5], v[86:87], v[2:3]
	v_rcp_f32_e32 v6, v23
	v_pk_mul_f32 v[10:11], v[4:5], v[4:5]
	v_mul_f32_e32 v7, v7, v23
	v_mov_b32_e32 v12, v10
	v_mul_f32_e32 v6, v51, v6
	v_cvt_pk_bf16_f32 v6, v6, s0
	v_mov_b32_dpp v12, v12 quad_perm:[1,0,3,2] row_mask:0xf bank_mask:0xf
	v_add_f32_e32 v10, v10, v12
	v_mov_b32_e32 v12, v10
	ds_write_b16 v119, v6 offset:32112
	s_nop 0
	v_mov_b32_dpp v12, v12 quad_perm:[2,3,0,1] row_mask:0xf bank_mask:0xf
	v_add_f32_e32 v10, v10, v12
	v_mov_b32_e32 v12, v10
	s_nop 1
	v_mov_b32_dpp v12, v12 row_half_mirror row_mask:0xf bank_mask:0xf
	v_add_f32_e32 v10, v10, v12
	v_mov_b32_e32 v12, v10
	s_nop 1
	v_mov_b32_dpp v12, v12 row_mirror row_mask:0xf bank_mask:0xf
	v_add_f32_e32 v10, v10, v12
	s_nop 0
	v_readlane_b32 s27, v10, 16
	v_readlane_b32 s30, v10, 48
	v_readlane_b32 s28, v10, 0
	v_readlane_b32 s29, v10, 32
	v_mov_b32_e32 v12, s27
	v_mov_b32_e32 v13, s30
	v_pk_add_f32 v[12:13], s[28:29], v[12:13]
	s_nop 0
	v_add_f32_e32 v10, v12, v13
	v_mov_b32_e32 v12, v11
	v_max_f32_e32 v10, 0x179abe15, v10
	v_rsq_f32_e32 v10, v10
	v_mov_b32_dpp v12, v12 quad_perm:[1,0,3,2] row_mask:0xf bank_mask:0xf
	v_add_f32_e32 v11, v11, v12
	v_mov_b32_e32 v12, v11
	s_nop 1
	v_mov_b32_dpp v12, v12 quad_perm:[2,3,0,1] row_mask:0xf bank_mask:0xf
	v_add_f32_e32 v11, v11, v12
	v_mov_b32_e32 v12, v11
	s_nop 1
	v_mov_b32_dpp v12, v12 row_half_mirror row_mask:0xf bank_mask:0xf
	v_add_f32_e32 v11, v11, v12
	v_mov_b32_e32 v12, v11
	s_nop 1
	v_mov_b32_dpp v12, v12 row_mirror row_mask:0xf bank_mask:0xf
	v_add_f32_e32 v11, v11, v12
	s_nop 0
	v_readlane_b32 s27, v11, 16
	v_readlane_b32 s30, v11, 48
	v_readlane_b32 s28, v11, 0
	v_readlane_b32 s29, v11, 32
	v_mov_b32_e32 v12, s27
	v_mov_b32_e32 v13, s30
	v_pk_add_f32 v[12:13], s[28:29], v[12:13]
	s_nop 0
	v_add_f32_e32 v11, v12, v13
	v_max_f32_e32 v11, 0x179abe15, v11
	v_rsq_f32_e32 v11, v11
	s_nop 0
	v_pk_mul_f32 v[4:5], v[4:5], v[10:11]
	s_nop 0
	v_mul_f32_e64 v157, v27, -v4
	v_pk_mul_f32 v[12:13], v[16:17], v[4:5]
	v_cvt_pk_bf16_f32 v4, v157, s0
	v_mul_f32_e32 v11, v3, v56
	v_mov_b32_e32 v3, v14
	ds_write_b16 v119, v4 offset:25056
	v_mul_f32_e32 v4, v14, v12
	v_pk_mul_f32 v[2:3], v[2:3], v[18:19]
	v_cvt_pk_bf16_f32 v4, v4, s0
	ds_write_b16 v119, v4 offset:27360
	v_mul_f32_e32 v4, v14, v2
	v_cvt_pk_bf16_f32 v6, v4, s0
	v_mul_f32_e32 v4, v150, v4
	v_cvt_pk_bf16_f32 v4, v4, s0
	v_mul_f32_e64 v156, v22, -v5
	ds_write_b16 v119, v6 offset:29664
	ds_write_b16 v107, v4 offset:20448
	v_cvt_pk_bf16_f32 v4, v156, s0
	ds_write_b16 v119, v4 offset:25200
	v_mul_f32_e32 v4, v23, v13
	v_cvt_pk_bf16_f32 v4, v4, s0
	v_mov_b32_e32 v6, v3
	ds_write_b16 v119, v4 offset:27504
	v_mul_f32_e32 v4, v23, v11
	v_pk_mul_f32 v[14:15], v[12:13], v[6:7]
	v_cvt_pk_bf16_f32 v5, v4, s0
	v_mul_f32_e32 v4, v150, v4
	v_mov_b32_e32 v6, v2
	v_mov_b32_e32 v10, v3
	v_cvt_pk_bf16_f32 v4, v4, s0
	v_pk_mul_f32 v[6:7], v[6:7], v[10:11]
	ds_write_b16 v119, v5 offset:29808
	ds_write_b16 v107, v4 offset:20592
	v_cvt_pk_bf16_f32 v2, v20, v21
	v_cvt_pk_bf16_f32 v3, v14, v15
	v_cvt_pk_bf16_f32 v4, v8, v9
	v_cvt_pk_bf16_f32 v5, v6, v7
	global_store_dwordx4 v[0:1], v[2:5], off offset:768 nt
	s_waitcnt lgkmcnt(0)
	ds_read2st64_b64 v[0:3], v100 offset1:1
	s_nop 0
	v_cndmask_b32_e32 v4, v155, v50, vcc
	v_add_u32_e32 v81, -1, v4
	ds_read2st64_b64 v[4:7], v100 offset0:2 offset1:3
	s_waitcnt lgkmcnt(1)
	v_bfe_u32 v0, v0, 16, 15
	v_add_u32_e32 v0, v0, v81
	v_bfe_u32 v2, v2, 16, 15
	v_max_i32_e32 v0, 0, v0
	s_waitcnt lgkmcnt(0)
	v_bfe_u32 v4, v4, 16, 15
	v_add_u32_e32 v4, v4, v81
	v_bfe_u32 v6, v6, 16, 15
	v_add_u32_e32 v2, v2, v81
	v_max_i32_e32 v4, 0, v4
	v_add_u32_e32 v6, v6, v81
	v_mad_u64_u32 v[8:9], s[28:29], v0, s24, v[194:195]
	v_ashrrev_i32_e32 v11, 31, v1
	v_mov_b32_e32 v10, v1
	v_max_i32_e32 v2, 0, v2
	v_mad_u64_u32 v[12:13], s[28:29], v4, s24, v[194:195]
	v_ashrrev_i32_e32 v15, 31, v5
	v_mov_b32_e32 v14, v5
	v_max_i32_e32 v6, 0, v6
	v_lshl_add_u64 v[0:1], v[10:11], 1, v[8:9]
	v_mad_u64_u32 v[8:9], s[28:29], v2, s24, v[194:195]
	v_ashrrev_i32_e32 v11, 31, v3
	v_mov_b32_e32 v10, v3
	v_lshl_add_u64 v[4:5], v[14:15], 1, v[12:13]
	v_mad_u64_u32 v[12:13], s[28:29], v6, s24, v[194:195]
	v_ashrrev_i32_e32 v15, 31, v7
	v_mov_b32_e32 v14, v7
	v_lshl_add_u64 v[2:3], v[10:11], 1, v[8:9]
	v_lshl_add_u64 v[6:7], v[14:15], 1, v[12:13]
	global_load_dwordx4 v[8:11], v[0:1], off nt
	s_nop 0
	global_load_dwordx4 v[0:3], v[2:3], off nt
	ds_read2st64_b64 v[16:19], v100 offset0:4 offset1:5
	global_load_dwordx4 v[12:15], v[4:5], off nt
	s_nop 0
	global_load_dwordx4 v[4:7], v[6:7], off nt
	ds_read2st64_b64 v[20:23], v100 offset0:6 offset1:7
	s_waitcnt lgkmcnt(1)
	v_bfe_u32 v16, v16, 16, 15
	v_add_u32_e32 v16, v16, v81
	s_waitcnt lgkmcnt(0)
	v_bfe_u32 v20, v20, 16, 15
	v_bfe_u32 v18, v18, 16, 15
	v_add_u32_e32 v20, v20, v81
	v_bfe_u32 v22, v22, 16, 15
	v_max_i32_e32 v16, 0, v16
	v_add_u32_e32 v18, v18, v81
	v_max_i32_e32 v20, 0, v20
	v_add_u32_e32 v22, v22, v81
	v_mad_u64_u32 v[24:25], s[28:29], v16, s24, v[194:195]
	v_ashrrev_i32_e32 v27, 31, v17
	v_mov_b32_e32 v26, v17
	v_max_i32_e32 v18, 0, v18
	v_mad_u64_u32 v[28:29], s[28:29], v20, s24, v[194:195]
	v_ashrrev_i32_e32 v31, 31, v21
	v_mov_b32_e32 v30, v21
	v_max_i32_e32 v22, 0, v22
	v_lshl_add_u64 v[16:17], v[26:27], 1, v[24:25]
	v_mad_u64_u32 v[24:25], s[28:29], v18, s24, v[194:195]
	v_ashrrev_i32_e32 v27, 31, v19
	v_mov_b32_e32 v26, v19
	v_lshl_add_u64 v[20:21], v[30:31], 1, v[28:29]
	v_mad_u64_u32 v[28:29], s[28:29], v22, s24, v[194:195]
	v_ashrrev_i32_e32 v31, 31, v23
	v_mov_b32_e32 v30, v23
	v_lshl_add_u64 v[18:19], v[26:27], 1, v[24:25]
	v_lshl_add_u64 v[22:23], v[30:31], 1, v[28:29]
	global_load_dwordx4 v[24:27], v[16:17], off nt
	s_nop 0
	global_load_dwordx4 v[16:19], v[18:19], off nt
	ds_read2st64_b64 v[32:35], v100 offset0:8 offset1:9
	global_load_dwordx4 v[28:31], v[20:21], off nt
	s_nop 0
	global_load_dwordx4 v[20:23], v[22:23], off nt
	ds_read_b64 v[196:197], v100 offset:5120
	ds_read_b128 v[36:39], v102 offset:23040
	ds_read_b128 v[40:43], v102 offset:23104
	ds_read_b128 v[52:55], v102 offset:25344
	ds_read_b128 v[56:59], v102 offset:25408
	ds_read_b128 v[60:63], v102 offset:27648
	ds_read_b128 v[182:185], v102 offset:29952
	ds_read_b128 v[186:189], v102 offset:27712
	ds_read_b128 v[190:193], v102 offset:30016
	s_waitcnt lgkmcnt(9)
	v_bfe_u32 v32, v32, 16, 15
	s_waitcnt lgkmcnt(5)
	v_mfma_f32_16x16x32_bf16 v[44:47], v[36:39], v[52:55], 0
	v_add_u32_e32 v32, v32, v81
	v_max_i32_e32 v32, 0, v32
	v_mad_u64_u32 v[48:49], s[28:29], v32, s24, v[194:195]
	s_waitcnt lgkmcnt(3)
	v_mfma_f32_16x16x32_bf16 v[36:39], v[36:39], v[60:63], 0
	v_ashrrev_i32_e32 v51, 31, v33
	v_mov_b32_e32 v50, v33
	v_lshl_add_u64 v[32:33], v[50:51], 1, v[48:49]
	s_waitcnt lgkmcnt(1)
	v_mfma_f32_16x16x32_bf16 v[48:51], v[40:43], v[186:189], v[36:39]
	v_bfe_u32 v34, v34, 16, 15
	v_add_u32_e32 v34, v34, v81
	v_max_i32_e32 v34, 0, v34
	v_mfma_f32_16x16x32_bf16 v[36:39], v[182:185], v[52:55], 0
	v_ashrrev_i32_e32 v199, 31, v197
	v_mov_b32_e32 v198, v197
	s_waitcnt lgkmcnt(0)
	v_mfma_f32_16x16x32_bf16 v[52:55], v[190:193], v[56:59], v[36:39]
	v_mfma_f32_16x16x32_bf16 v[44:47], v[40:43], v[56:59], v[44:47]
	s_nop 2
	v_bfe_u32 v36, v196, 16, 15
	v_add_u32_e32 v36, v36, v81
	v_max_i32_e32 v56, 0, v36
	v_mfma_f32_16x16x32_bf16 v[36:39], v[182:185], v[60:63], 0
	v_mad_u64_u32 v[40:41], s[28:29], v34, s24, v[194:195]
	v_ashrrev_i32_e32 v43, 31, v35
	v_mov_b32_e32 v42, v35
	v_mad_u64_u32 v[194:195], s[28:29], v56, s24, v[194:195]
	v_lshl_add_u64 v[34:35], v[42:43], 1, v[40:41]
	v_mfma_f32_16x16x32_bf16 v[56:59], v[190:193], v[186:189], v[36:39]
	global_load_dwordx4 v[40:43], v[32:33], off nt
	s_nop 0
	global_load_dwordx4 v[32:35], v[34:35], off nt
	v_lshl_add_u64 v[36:37], v[198:199], 1, v[194:195]
	global_load_dwordx4 v[36:39], v[36:37], off nt
	ds_read_b128 v[60:63], v102 offset:18432
	ds_read_b128 v[186:189], v102 offset:18496
	s_waitcnt lgkmcnt(1)
	v_mfma_f32_16x16x32_bf16 v[60:63], v[182:185], v[60:63], 0
	s_waitcnt lgkmcnt(0)
	v_mfma_f32_16x16x32_bf16 v[60:63], v[190:193], v[186:189], v[60:63]
	s_and_saveexec_b64 s[58:59], s[38:39]
	s_cbranch_execz .LBB0_1032
	v_cmp_lt_i32_e32 vcc, 0, v103
	s_and_saveexec_b64 s[28:29], vcc
	s_xor_b64 s[60:61], exec, s[28:29]
	s_cbranch_execz .LBB0_1031
	v_cmp_ne_u32_e32 vcc, 1, v103
	s_nop 0
	v_mov_b32_e32 v60, v61
	s_and_saveexec_b64 s[28:29], vcc
	s_xor_b64 s[62:63], exec, s[28:29]
	v_cndmask_b32_e64 v60, v63, v62, s[40:41]
	s_andn2_saveexec_b64 s[62:63], s[62:63]
	s_or_b64 exec, exec, s[62:63]
.LBB0_1031:
	s_andn2_saveexec_b64 s[60:61], s[60:61]
	s_or_b64 exec, exec, s[60:61]
	v_mov_b32_e32 v81, v145
	v_lshl_add_u64 v[62:63], v[88:89], 0, v[80:81]
	v_add_co_u32_e32 v62, vcc, 0x3000, v62
	s_nop 1
	v_addc_co_u32_e32 v63, vcc, 0, v63, vcc
	global_store_dword v[62:63], v60, off offset:256 nt
